# v17 + FFN-up K-loops: in the two SP2-type segments the A half-tile's two LDS-DMA pieces are issued between the two MFMA blocks instead of in the load segment; the wait before that barrier keeps 6 inst
# baseline (speedup 1.0000x reference)
; #define PG8_STAGE(bufoff, gbase, voff) do { _Pragma("unroll") for (int _i = 0; _i < 2; ++_i) \
;         __builtin_amdgcn_global_load_lds((const unsigned*)((const char*)(gbase) + (voff)[_i]), (PG8_LAS unsigned*)(lds + (bufoff) + ldsw + _i * 8192), 16, 0, 0); } while (0)
; #define PG8_WAIT_V(n) asm volatile("s_waitcnt vmcnt(" #n ")" ::: "memory")
; #define PG8_WAIT_L(n) asm volatile("s_waitcnt lgkmcnt(" #n ")" ::: "memory")
; #define PG8_BAR __builtin_amdgcn_s_barrier()
; #define PG8_SCHED __builtin_amdgcn_sched_barrier(0)
; template <class Epi, class Sched, bool ALIGN_EPI = true, bool SP2 = true>
; __device__ __forceinline__ void gemm_phase(PG8_LAS unsigned char* lds, const int K  , const Sched& S, const Epi& E) {
;     ...
;             PG8_LDB(B0, 0, 0); PG8_LDB(B1, 0, 1); PG8_SCHED; PG8_LDA(At, 0, 0); PG8_STAGE(PG8_SA(1, 1), a1 + hstep, voffA);
;             PG8_WAIT_V(8); PG8_WAIT_L(0); PG8_BAR; PG8_MMA(0, 0, At, B0); PG8_MMA(0, 1, At, B1); PG8_BAR; PG8_SCHED;
;             PG8_LDA(At, 0, 1); PG8_STAGE(PG8_SB(0, 0), b2, voffB); PG8_STAGE(PG8_SB(0, 1), b2 + hstep, voffB); PG8_STAGE(PG8_SA(0, 0), a2, voffA);
;             PG8_WAIT_V(8); PG8_WAIT_L(0); PG8_BAR; PG8_MMA(1, 0, At, B0); PG8_MMA(1, 1, At, B1); PG8_BAR; PG8_SCHED;
.LBB0_219:
	ds_read_b128 v[148:151], v154
	ds_read_b128 v[160:163], v154 offset:1024
	ds_read_b128 v[164:167], v154 offset:2048
	ds_read_b128 v[168:171], v154 offset:3072
	ds_read_b128 v[172:175], v155
	ds_read_b128 v[176:179], v155 offset:1024
	ds_read_b128 v[180:183], v155 offset:2048
	ds_read_b128 v[184:187], v155 offset:3072
	s_add_u32 s22, s20, 0xfff80080
	s_addc_u32 s23, s21, -1
	s_cmp_eq_u32 s48, 28
	s_cselect_b32 s25, s13, s23
	s_cselect_b32 s24, s44, s22
	s_cselect_b32 s23, s11, s47
	s_cselect_b32 s22, s45, s46
	v_lshl_add_u64 v[220:221], s[20:21], 0, v[140:141]
	s_add_i32 m0, s19, 0xc000
	ds_read_b128 v[188:191], v156
	ds_read_b128 v[192:195], v156 offset:1024
	ds_read_b128 v[196:199], v156 offset:2048
	ds_read_b128 v[200:203], v156 offset:3072
	ds_read_b128 v[204:207], v156 offset:4096
	ds_read_b128 v[208:211], v156 offset:5120
	ds_read_b128 v[212:215], v156 offset:6144
	ds_read_b128 v[216:219], v156 offset:7168
	global_load_lds_dwordx4 v[220:221], off
	v_lshl_add_u64 v[220:221], s[20:21], 0, v[142:143]
	s_add_i32 m0, s19, 0xe000
	s_nop 0
	global_load_lds_dwordx4 v[220:221], off
	s_waitcnt vmcnt(8)
	s_waitcnt lgkmcnt(0)
	s_barrier
	s_setprio 1
	s_waitcnt lgkmcnt(0)
	v_mfma_f32_16x16x32_bf16 v[126:129], v[148:151], v[188:191], v[126:129]
	v_mfma_f32_16x16x32_bf16 v[118:121], v[164:167], v[188:191], v[118:121]
	v_mfma_f32_16x16x32_bf16 v[110:113], v[148:151], v[196:199], v[110:113]
	v_mfma_f32_16x16x32_bf16 v[102:105], v[164:167], v[196:199], v[102:105]
	v_mfma_f32_16x16x32_bf16 v[94:97], v[148:151], v[204:207], v[94:97]
	v_mfma_f32_16x16x32_bf16 v[86:89], v[164:167], v[204:207], v[86:89]
	v_mfma_f32_16x16x32_bf16 v[78:81], v[148:151], v[212:215], v[78:81]
	v_mfma_f32_16x16x32_bf16 v[70:73], v[164:167], v[212:215], v[70:73]
	v_mfma_f32_16x16x32_bf16 v[126:129], v[160:163], v[192:195], v[126:129]
	v_mfma_f32_16x16x32_bf16 v[118:121], v[168:171], v[192:195], v[118:121]
	v_mfma_f32_16x16x32_bf16 v[110:113], v[160:163], v[200:203], v[110:113]
	v_mfma_f32_16x16x32_bf16 v[102:105], v[168:171], v[200:203], v[102:105]
	v_mfma_f32_16x16x32_bf16 v[94:97], v[160:163], v[208:211], v[94:97]
	v_mfma_f32_16x16x32_bf16 v[86:89], v[168:171], v[208:211], v[86:89]
	v_mfma_f32_16x16x32_bf16 v[78:81], v[160:163], v[216:219], v[78:81]
	v_mfma_f32_16x16x32_bf16 v[70:73], v[168:171], v[216:219], v[70:73]
	s_setprio 0
	s_setprio 1
	v_mfma_f32_16x16x32_bf16 v[122:125], v[172:175], v[188:191], v[122:125]
	v_mfma_f32_16x16x32_bf16 v[114:117], v[180:183], v[188:191], v[114:117]
	v_mfma_f32_16x16x32_bf16 v[106:109], v[172:175], v[196:199], v[106:109]
	v_mfma_f32_16x16x32_bf16 v[98:101], v[180:183], v[196:199], v[98:101]
	v_mfma_f32_16x16x32_bf16 v[90:93], v[172:175], v[204:207], v[90:93]
	v_mfma_f32_16x16x32_bf16 v[82:85], v[180:183], v[204:207], v[82:85]
	v_mfma_f32_16x16x32_bf16 v[74:77], v[172:175], v[212:215], v[74:77]
	v_mfma_f32_16x16x32_bf16 v[66:69], v[180:183], v[212:215], v[66:69]
	v_mfma_f32_16x16x32_bf16 v[122:125], v[176:179], v[192:195], v[122:125]
	v_mfma_f32_16x16x32_bf16 v[114:117], v[184:187], v[192:195], v[114:117]
	v_mfma_f32_16x16x32_bf16 v[106:109], v[176:179], v[200:203], v[106:109]
	v_mfma_f32_16x16x32_bf16 v[98:101], v[184:187], v[200:203], v[98:101]
	v_mfma_f32_16x16x32_bf16 v[90:93], v[176:179], v[208:211], v[90:93]
	v_mfma_f32_16x16x32_bf16 v[82:85], v[184:187], v[208:211], v[82:85]
	v_mfma_f32_16x16x32_bf16 v[74:77], v[176:179], v[216:219], v[74:77]
	v_mfma_f32_16x16x32_bf16 v[66:69], v[184:187], v[216:219], v[66:69]
	s_setprio 0
	s_barrier
	s_add_i32 s49, s39, s29
	v_lshl_add_u64 v[220:221], s[22:23], 0, v[136:137]
	s_mov_b32 m0, s49
	ds_read_b128 v[188:191], v156 offset:16384
	ds_read_b128 v[192:195], v156 offset:17408
	ds_read_b128 v[196:199], v156 offset:18432
	ds_read_b128 v[200:203], v156 offset:19456
	ds_read_b128 v[204:207], v156 offset:20480
	ds_read_b128 v[208:211], v156 offset:21504
	ds_read_b128 v[212:215], v156 offset:22528
	ds_read_b128 v[216:219], v156 offset:23552
	global_load_lds_dwordx4 v[220:221], off
	s_add_i32 m0, s49, 0x2000
	s_add_u32 s50, s22, 0x80000
	v_lshl_add_u64 v[222:223], s[22:23], 0, v[132:133]
	s_addc_u32 s51, s23, 0
	s_add_i32 s49, s40, s29
	global_load_lds_dwordx4 v[222:223], off
	v_lshl_add_u64 v[224:225], s[50:51], 0, v[136:137]
	s_mov_b32 m0, s49
	v_lshl_add_u64 v[226:227], s[24:25], 0, v[134:135]
	global_load_lds_dwordx4 v[224:225], off
	v_lshl_add_u64 v[224:225], s[50:51], 0, v[132:133]
	s_add_i32 m0, s49, 0x2000
	s_nop 0
	global_load_lds_dwordx4 v[224:225], off
	s_waitcnt vmcnt(6)
	s_waitcnt lgkmcnt(0)
	s_barrier
; #define PG8_STAGE(bufoff, gbase, voff) do { _Pragma("unroll") for (int _i = 0; _i < 2; ++_i) \
;         __builtin_amdgcn_global_load_lds((const unsigned*)((const char*)(gbase) + (voff)[_i]), (PG8_LAS unsigned*)(lds + (bufoff) + ldsw + _i * 8192), 16, 0, 0); } while (0)
; #define PG8_WAIT_V(n) asm volatile("s_waitcnt vmcnt(" #n ")" ::: "memory")
; #define PG8_WAIT_L(n) asm volatile("s_waitcnt lgkmcnt(" #n ")" ::: "memory")
; #define PG8_BAR __builtin_amdgcn_s_barrier()
; #define PG8_SCHED __builtin_amdgcn_sched_barrier(0)
; template <class Epi, class Sched, bool ALIGN_EPI = true, bool SP2 = true>
; __device__ __forceinline__ void gemm_phase(PG8_LAS unsigned char* lds, const int K  , const Sched& S, const Epi& E) {
;     ...
;             PG8_WAIT_V(8); PG8_WAIT_L(0); PG8_BAR; PG8_MMA(1, 0, At, B0); PG8_MMA(1, 1, At, B1); PG8_BAR; PG8_SCHED;
;             PG8_LDB(B0, 1, 0); PG8_LDB(B1, 1, 1); PG8_SCHED; PG8_LDA(At, 1, 0); PG8_STAGE(PG8_SA(0, 1), a2 + hstep, voffA);
;             PG8_WAIT_V(8); PG8_WAIT_L(0); PG8_BAR; PG8_MMA(0, 0, At, B0); PG8_MMA(0, 1, At, B1); PG8_BAR; PG8_SCHED;
	s_setprio 1
	s_waitcnt lgkmcnt(0)
	v_mfma_f32_16x16x32_bf16 v[62:65], v[148:151], v[188:191], v[62:65]
	v_mfma_f32_16x16x32_bf16 v[54:57], v[164:167], v[188:191], v[54:57]
	v_mfma_f32_16x16x32_bf16 v[46:49], v[148:151], v[196:199], v[46:49]
	v_mfma_f32_16x16x32_bf16 v[38:41], v[164:167], v[196:199], v[38:41]
	v_mfma_f32_16x16x32_bf16 v[30:33], v[148:151], v[204:207], v[30:33]
	v_mfma_f32_16x16x32_bf16 v[22:25], v[164:167], v[204:207], v[22:25]
	v_mfma_f32_16x16x32_bf16 v[14:17], v[148:151], v[212:215], v[14:17]
	v_mfma_f32_16x16x32_bf16 v[6:9], v[164:167], v[212:215], v[6:9]
	v_mfma_f32_16x16x32_bf16 v[62:65], v[160:163], v[192:195], v[62:65]
	v_mfma_f32_16x16x32_bf16 v[54:57], v[168:171], v[192:195], v[54:57]
	v_mfma_f32_16x16x32_bf16 v[46:49], v[160:163], v[200:203], v[46:49]
	v_mfma_f32_16x16x32_bf16 v[38:41], v[168:171], v[200:203], v[38:41]
	v_mfma_f32_16x16x32_bf16 v[30:33], v[160:163], v[208:211], v[30:33]
	v_mfma_f32_16x16x32_bf16 v[22:25], v[168:171], v[208:211], v[22:25]
	v_mfma_f32_16x16x32_bf16 v[14:17], v[160:163], v[216:219], v[14:17]
	v_mfma_f32_16x16x32_bf16 v[6:9], v[168:171], v[216:219], v[6:9]
	v_lshl_add_u64 v[224:225], s[24:25], 0, v[138:139]
	s_mov_b32 m0, s19
	s_nop 0
	global_load_lds_dwordx4 v[224:225], off
	s_mov_b32 m0, s31
	s_nop 0
	global_load_lds_dwordx4 v[226:227], off
	v_mfma_f32_16x16x32_bf16 v[58:61], v[172:175], v[188:191], v[58:61]
	v_mfma_f32_16x16x32_bf16 v[50:53], v[180:183], v[188:191], v[50:53]
	v_mfma_f32_16x16x32_bf16 v[42:45], v[172:175], v[196:199], v[42:45]
	v_mfma_f32_16x16x32_bf16 v[34:37], v[180:183], v[196:199], v[34:37]
	v_mfma_f32_16x16x32_bf16 v[26:29], v[172:175], v[204:207], v[26:29]
	v_mfma_f32_16x16x32_bf16 v[18:21], v[180:183], v[204:207], v[18:21]
	v_mfma_f32_16x16x32_bf16 v[10:13], v[172:175], v[212:215], v[10:13]
	v_mfma_f32_16x16x32_bf16 v[2:5], v[180:183], v[212:215], v[2:5]
	v_mfma_f32_16x16x32_bf16 v[58:61], v[176:179], v[192:195], v[58:61]
	v_mfma_f32_16x16x32_bf16 v[50:53], v[184:187], v[192:195], v[50:53]
	v_mfma_f32_16x16x32_bf16 v[42:45], v[176:179], v[200:203], v[42:45]
	v_mfma_f32_16x16x32_bf16 v[34:37], v[184:187], v[200:203], v[34:37]
	v_mfma_f32_16x16x32_bf16 v[26:29], v[176:179], v[208:211], v[26:29]
	v_mfma_f32_16x16x32_bf16 v[18:21], v[184:187], v[208:211], v[18:21]
	v_mfma_f32_16x16x32_bf16 v[10:13], v[176:179], v[216:219], v[10:13]
	v_mfma_f32_16x16x32_bf16 v[2:5], v[184:187], v[216:219], v[2:5]
	s_setprio 0
	s_barrier
	s_add_i32 s49, 0, 0x18000
	v_add_u32_e32 v159, s49, v152
	s_add_i32 s50, 0, 0x1c000
	ds_read_b128 v[148:151], v159
	ds_read_b128 v[160:163], v159 offset:1024
	ds_read_b128 v[164:167], v159 offset:2048
	ds_read_b128 v[168:171], v159 offset:3072
	v_add_u32_e32 v159, s50, v152
	ds_read_b128 v[172:175], v159
	ds_read_b128 v[176:179], v159 offset:1024
	ds_read_b128 v[180:183], v159 offset:2048
	ds_read_b128 v[184:187], v159 offset:3072
	s_add_u32 s24, s24, 0x80000
	s_addc_u32 s25, s25, 0
	s_mov_b32 m0, s33
	v_lshl_add_u64 v[230:231], s[24:25], 0, v[138:139]
	ds_read_b128 v[188:191], v156 offset:32768
	ds_read_b128 v[192:195], v156 offset:33792
	ds_read_b128 v[196:199], v156 offset:34816
	ds_read_b128 v[200:203], v156 offset:35840
	ds_read_b128 v[204:207], v156 offset:36864
	ds_read_b128 v[208:211], v156 offset:37888
	ds_read_b128 v[212:215], v156 offset:38912
	ds_read_b128 v[216:219], v156 offset:39936
	global_load_lds_dwordx4 v[230:231], off
	v_lshl_add_u64 v[230:231], s[24:25], 0, v[134:135]
	s_mov_b32 m0, s34
	s_nop 0
	global_load_lds_dwordx4 v[230:231], off
	s_waitcnt vmcnt(8)
	s_waitcnt lgkmcnt(0)
	s_barrier
	s_setprio 1
	s_waitcnt lgkmcnt(0)
	v_mfma_f32_16x16x32_bf16 v[126:129], v[148:151], v[188:191], v[126:129]
	v_mfma_f32_16x16x32_bf16 v[118:121], v[164:167], v[188:191], v[118:121]
	v_mfma_f32_16x16x32_bf16 v[110:113], v[148:151], v[196:199], v[110:113]
	v_mfma_f32_16x16x32_bf16 v[102:105], v[164:167], v[196:199], v[102:105]
	v_mfma_f32_16x16x32_bf16 v[94:97], v[148:151], v[204:207], v[94:97]
	v_mfma_f32_16x16x32_bf16 v[86:89], v[164:167], v[204:207], v[86:89]
	v_mfma_f32_16x16x32_bf16 v[78:81], v[148:151], v[212:215], v[78:81]
	v_mfma_f32_16x16x32_bf16 v[70:73], v[164:167], v[212:215], v[70:73]
	v_mfma_f32_16x16x32_bf16 v[126:129], v[160:163], v[192:195], v[126:129]
	v_mfma_f32_16x16x32_bf16 v[118:121], v[168:171], v[192:195], v[118:121]
	v_mfma_f32_16x16x32_bf16 v[110:113], v[160:163], v[200:203], v[110:113]
	v_mfma_f32_16x16x32_bf16 v[102:105], v[168:171], v[200:203], v[102:105]
	v_mfma_f32_16x16x32_bf16 v[94:97], v[160:163], v[208:211], v[94:97]
	v_mfma_f32_16x16x32_bf16 v[86:89], v[168:171], v[208:211], v[86:89]
	v_mfma_f32_16x16x32_bf16 v[78:81], v[160:163], v[216:219], v[78:81]
	v_mfma_f32_16x16x32_bf16 v[70:73], v[168:171], v[216:219], v[70:73]
	s_setprio 0
	s_setprio 1
	v_mfma_f32_16x16x32_bf16 v[122:125], v[172:175], v[188:191], v[122:125]
	v_mfma_f32_16x16x32_bf16 v[114:117], v[180:183], v[188:191], v[114:117]
	v_mfma_f32_16x16x32_bf16 v[106:109], v[172:175], v[196:199], v[106:109]
	v_mfma_f32_16x16x32_bf16 v[98:101], v[180:183], v[196:199], v[98:101]
	v_mfma_f32_16x16x32_bf16 v[90:93], v[172:175], v[204:207], v[90:93]
	v_mfma_f32_16x16x32_bf16 v[82:85], v[180:183], v[204:207], v[82:85]
	v_mfma_f32_16x16x32_bf16 v[74:77], v[172:175], v[212:215], v[74:77]
	v_mfma_f32_16x16x32_bf16 v[66:69], v[180:183], v[212:215], v[66:69]
	v_mfma_f32_16x16x32_bf16 v[122:125], v[176:179], v[192:195], v[122:125]
	v_mfma_f32_16x16x32_bf16 v[114:117], v[184:187], v[192:195], v[114:117]
	v_mfma_f32_16x16x32_bf16 v[106:109], v[176:179], v[200:203], v[106:109]
	v_mfma_f32_16x16x32_bf16 v[98:101], v[184:187], v[200:203], v[98:101]
	v_mfma_f32_16x16x32_bf16 v[90:93], v[176:179], v[208:211], v[90:93]
	v_mfma_f32_16x16x32_bf16 v[82:85], v[184:187], v[208:211], v[82:85]
	v_mfma_f32_16x16x32_bf16 v[74:77], v[176:179], v[216:219], v[74:77]
	v_mfma_f32_16x16x32_bf16 v[66:69], v[184:187], v[216:219], v[66:69]
	s_setprio 0
	s_barrier
; #define PG8_STAGE(bufoff, gbase, voff) do { _Pragma("unroll") for (int _i = 0; _i < 2; ++_i) \
;         __builtin_amdgcn_global_load_lds((const unsigned*)((const char*)(gbase) + (voff)[_i]), (PG8_LAS unsigned*)(lds + (bufoff) + ldsw + _i * 8192), 16, 0, 0); } while (0)
; #define PG8_WAIT_V(n) asm volatile("s_waitcnt vmcnt(" #n ")" ::: "memory")
; #define PG8_WAIT_L(n) asm volatile("s_waitcnt lgkmcnt(" #n ")" ::: "memory")
; #define PG8_BAR __builtin_amdgcn_s_barrier()
; #define PG8_SCHED __builtin_amdgcn_sched_barrier(0)
;     __device__ __forceinline__ int nt(const pg8::Unit& u) const { return u.kind == 0 ? ntiles : q_nt(u.kind - 1); }
; template <class Epi, class Sched, bool ALIGN_EPI = true, bool SP2 = true>
; __device__ __forceinline__ void gemm_phase(PG8_LAS unsigned char* lds, const int K  , const Sched& S, const Epi& E) {
;     ...
;         for (int t = 0; t < nt; t += 2) {
;     ...
;             PG8_LDA(At, 1, 1); PG8_STAGE(PG8_SB(1, 0), b3, voffB); PG8_STAGE(PG8_SB(1, 1), b3 + hstep, voffB); PG8_STAGE(PG8_SA(1, 0), a3, voffA);
;             PG8_WAIT_V(8); PG8_WAIT_L(0); PG8_BAR; PG8_MMA(1, 0, At, B0); PG8_MMA(1, 1, At, B1); PG8_BAR; PG8_SCHED;
	s_add_i32 s24, s49, s29
	v_lshl_add_u64 v[220:221], v[220:221], 0, s[6:7]
	s_mov_b32 m0, s24
	ds_read_b128 v[188:191], v156 offset:49152
	ds_read_b128 v[192:195], v156 offset:50176
	ds_read_b128 v[196:199], v156 offset:51200
	ds_read_b128 v[200:203], v156 offset:52224
	ds_read_b128 v[204:207], v156 offset:53248
	ds_read_b128 v[208:211], v156 offset:54272
	ds_read_b128 v[212:215], v156 offset:55296
	ds_read_b128 v[216:219], v156 offset:56320
	global_load_lds_dwordx4 v[220:221], off
	s_add_i32 m0, s24, 0x2000
	s_add_u32 s22, s22, 0x80080
	v_lshl_add_u64 v[220:221], v[222:223], 0, s[6:7]
	s_addc_u32 s23, s23, 0
	s_add_i32 s24, s50, s29
	global_load_lds_dwordx4 v[220:221], off
	v_lshl_add_u64 v[220:221], s[22:23], 0, v[136:137]
	s_mov_b32 m0, s24
	s_nop 0
	global_load_lds_dwordx4 v[220:221], off
	v_lshl_add_u64 v[220:221], s[22:23], 0, v[132:133]
	s_add_i32 m0, s24, 0x2000
	s_nop 0
	global_load_lds_dwordx4 v[220:221], off
	s_waitcnt vmcnt(6)
	s_waitcnt lgkmcnt(0)
	s_barrier
	s_setprio 1
	s_waitcnt lgkmcnt(0)
	v_mfma_f32_16x16x32_bf16 v[62:65], v[148:151], v[188:191], v[62:65]
	v_mfma_f32_16x16x32_bf16 v[54:57], v[164:167], v[188:191], v[54:57]
	v_mfma_f32_16x16x32_bf16 v[46:49], v[148:151], v[196:199], v[46:49]
	v_mfma_f32_16x16x32_bf16 v[38:41], v[164:167], v[196:199], v[38:41]
	v_mfma_f32_16x16x32_bf16 v[30:33], v[148:151], v[204:207], v[30:33]
	v_mfma_f32_16x16x32_bf16 v[22:25], v[164:167], v[204:207], v[22:25]
	v_mfma_f32_16x16x32_bf16 v[14:17], v[148:151], v[212:215], v[14:17]
	v_mfma_f32_16x16x32_bf16 v[6:9], v[164:167], v[212:215], v[6:9]
	v_mfma_f32_16x16x32_bf16 v[62:65], v[160:163], v[192:195], v[62:65]
	v_mfma_f32_16x16x32_bf16 v[54:57], v[168:171], v[192:195], v[54:57]
	v_mfma_f32_16x16x32_bf16 v[46:49], v[160:163], v[200:203], v[46:49]
	v_mfma_f32_16x16x32_bf16 v[38:41], v[168:171], v[200:203], v[38:41]
	v_mfma_f32_16x16x32_bf16 v[30:33], v[160:163], v[208:211], v[30:33]
	v_mfma_f32_16x16x32_bf16 v[22:25], v[168:171], v[208:211], v[22:25]
	v_mfma_f32_16x16x32_bf16 v[14:17], v[160:163], v[216:219], v[14:17]
	v_mfma_f32_16x16x32_bf16 v[6:9], v[168:171], v[216:219], v[6:9]
	v_lshl_add_u64 v[220:221], v[224:225], 0, s[6:7]
	s_mov_b32 m0, s36
	s_nop 0
	global_load_lds_dwordx4 v[220:221], off
	v_lshl_add_u64 v[220:221], v[226:227], 0, s[6:7]
	s_mov_b32 m0, s37
	s_nop 0
	global_load_lds_dwordx4 v[220:221], off
	v_mfma_f32_16x16x32_bf16 v[58:61], v[172:175], v[188:191], v[58:61]
	v_mfma_f32_16x16x32_bf16 v[50:53], v[180:183], v[188:191], v[50:53]
	v_mfma_f32_16x16x32_bf16 v[42:45], v[172:175], v[196:199], v[42:45]
	v_mfma_f32_16x16x32_bf16 v[34:37], v[180:183], v[196:199], v[34:37]
	v_mfma_f32_16x16x32_bf16 v[26:29], v[172:175], v[204:207], v[26:29]
	v_mfma_f32_16x16x32_bf16 v[18:21], v[180:183], v[204:207], v[18:21]
	v_mfma_f32_16x16x32_bf16 v[10:13], v[172:175], v[212:215], v[10:13]
	v_mfma_f32_16x16x32_bf16 v[2:5], v[180:183], v[212:215], v[2:5]
	v_mfma_f32_16x16x32_bf16 v[58:61], v[176:179], v[192:195], v[58:61]
	v_mfma_f32_16x16x32_bf16 v[50:53], v[184:187], v[192:195], v[50:53]
	v_mfma_f32_16x16x32_bf16 v[42:45], v[176:179], v[200:203], v[42:45]
	v_mfma_f32_16x16x32_bf16 v[34:37], v[184:187], v[200:203], v[34:37]
	v_mfma_f32_16x16x32_bf16 v[26:29], v[176:179], v[208:211], v[26:29]
	v_mfma_f32_16x16x32_bf16 v[18:21], v[184:187], v[208:211], v[18:21]
	v_mfma_f32_16x16x32_bf16 v[10:13], v[176:179], v[216:219], v[10:13]
	v_mfma_f32_16x16x32_bf16 v[2:5], v[184:187], v[216:219], v[2:5]
	s_setprio 0
	s_barrier
	s_add_i32 s48, s48, 2
	s_add_u32 s20, s20, 0x100
	s_addc_u32 s21, s21, 0
	s_add_u32 s46, s46, 0x100
	s_addc_u32 s47, s47, 0
	s_cmp_gt_u32 s48, 29
	s_cbranch_scc0 .LBB0_219
	s_and_b64 vcc, exec, s[8:9]
	s_cbranch_vccz .LBB0_222
	s_barrier

; #define PG8_STAGE(bufoff, gbase, voff) do { _Pragma("unroll") for (int _i = 0; _i < 2; ++_i) \
;         __builtin_amdgcn_global_load_lds((const unsigned*)((const char*)(gbase) + (voff)[_i]), (PG8_LAS unsigned*)(lds + (bufoff) + ldsw + _i * 8192), 16, 0, 0); } while (0)
; #define PG8_WAIT_V(n) asm volatile("s_waitcnt vmcnt(" #n ")" ::: "memory")
; #define PG8_WAIT_L(n) asm volatile("s_waitcnt lgkmcnt(" #n ")" ::: "memory")
; #define PG8_BAR __builtin_amdgcn_s_barrier()
; #define PG8_SCHED __builtin_amdgcn_sched_barrier(0)
; template <class Epi, class Sched, bool ALIGN_EPI = true, bool SP2 = true>
; __device__ __forceinline__ void gemm_phase(PG8_LAS unsigned char* lds, const int K  , const Sched& S, const Epi& E) {
;     ...
;             PG8_LDB(B0, 0, 0); PG8_LDB(B1, 0, 1); PG8_SCHED; PG8_LDA(At, 0, 0); PG8_STAGE(PG8_SA(1, 1), a1 + hstep, voffA);
;             PG8_WAIT_V(8); PG8_WAIT_L(0); PG8_BAR; PG8_MMA(0, 0, At, B0); PG8_MMA(0, 1, At, B1); PG8_BAR; PG8_SCHED;
;             PG8_LDA(At, 0, 1); PG8_STAGE(PG8_SB(0, 0), b2, voffB); PG8_STAGE(PG8_SB(0, 1), b2 + hstep, voffB); PG8_STAGE(PG8_SA(0, 0), a2, voffA);
;             PG8_WAIT_V(8); PG8_WAIT_L(0); PG8_BAR; PG8_MMA(1, 0, At, B0); PG8_MMA(1, 1, At, B1); PG8_BAR; PG8_SCHED;
.LBB0_1099:
	ds_read_b128 v[148:151], v154
	ds_read_b128 v[160:163], v154 offset:1024
	ds_read_b128 v[164:167], v154 offset:2048
	ds_read_b128 v[168:171], v154 offset:3072
	ds_read_b128 v[172:175], v155
	ds_read_b128 v[176:179], v155 offset:1024
	ds_read_b128 v[180:183], v155 offset:2048
	ds_read_b128 v[184:187], v155 offset:3072
	s_add_u32 s24, s22, 0xfff80080
	s_addc_u32 s25, s23, -1
	s_cmp_eq_u32 s48, 28
	s_cselect_b32 s27, s15, s25
	s_cselect_b32 s26, s44, s24
	s_cselect_b32 s25, s11, s47
	s_cselect_b32 s24, s45, s46
	v_lshl_add_u64 v[220:221], s[22:23], 0, v[140:141]
	s_add_i32 m0, s21, 0xc000
	ds_read_b128 v[188:191], v156
	ds_read_b128 v[192:195], v156 offset:1024
	ds_read_b128 v[196:199], v156 offset:2048
	ds_read_b128 v[200:203], v156 offset:3072
	ds_read_b128 v[204:207], v156 offset:4096
	ds_read_b128 v[208:211], v156 offset:5120
	ds_read_b128 v[212:215], v156 offset:6144
	ds_read_b128 v[216:219], v156 offset:7168
	global_load_lds_dwordx4 v[220:221], off
	v_lshl_add_u64 v[220:221], s[22:23], 0, v[142:143]
	s_add_i32 m0, s21, 0xe000
	s_nop 0
	global_load_lds_dwordx4 v[220:221], off
	s_waitcnt vmcnt(8)
	s_waitcnt lgkmcnt(0)
	s_barrier
	s_setprio 1
	s_waitcnt lgkmcnt(0)
	v_mfma_f32_16x16x32_bf16 v[126:129], v[148:151], v[188:191], v[126:129]
	v_mfma_f32_16x16x32_bf16 v[118:121], v[164:167], v[188:191], v[118:121]
	v_mfma_f32_16x16x32_bf16 v[110:113], v[148:151], v[196:199], v[110:113]
	v_mfma_f32_16x16x32_bf16 v[102:105], v[164:167], v[196:199], v[102:105]
	v_mfma_f32_16x16x32_bf16 v[94:97], v[148:151], v[204:207], v[94:97]
	v_mfma_f32_16x16x32_bf16 v[86:89], v[164:167], v[204:207], v[86:89]
	v_mfma_f32_16x16x32_bf16 v[78:81], v[148:151], v[212:215], v[78:81]
	v_mfma_f32_16x16x32_bf16 v[70:73], v[164:167], v[212:215], v[70:73]
	v_mfma_f32_16x16x32_bf16 v[126:129], v[160:163], v[192:195], v[126:129]
	v_mfma_f32_16x16x32_bf16 v[118:121], v[168:171], v[192:195], v[118:121]
	v_mfma_f32_16x16x32_bf16 v[110:113], v[160:163], v[200:203], v[110:113]
	v_mfma_f32_16x16x32_bf16 v[102:105], v[168:171], v[200:203], v[102:105]
	v_mfma_f32_16x16x32_bf16 v[94:97], v[160:163], v[208:211], v[94:97]
	v_mfma_f32_16x16x32_bf16 v[86:89], v[168:171], v[208:211], v[86:89]
	v_mfma_f32_16x16x32_bf16 v[78:81], v[160:163], v[216:219], v[78:81]
	v_mfma_f32_16x16x32_bf16 v[70:73], v[168:171], v[216:219], v[70:73]
	s_setprio 0
	s_setprio 1
	v_mfma_f32_16x16x32_bf16 v[122:125], v[172:175], v[188:191], v[122:125]
	v_mfma_f32_16x16x32_bf16 v[114:117], v[180:183], v[188:191], v[114:117]
	v_mfma_f32_16x16x32_bf16 v[106:109], v[172:175], v[196:199], v[106:109]
	v_mfma_f32_16x16x32_bf16 v[98:101], v[180:183], v[196:199], v[98:101]
	v_mfma_f32_16x16x32_bf16 v[90:93], v[172:175], v[204:207], v[90:93]
	v_mfma_f32_16x16x32_bf16 v[82:85], v[180:183], v[204:207], v[82:85]
	v_mfma_f32_16x16x32_bf16 v[74:77], v[172:175], v[212:215], v[74:77]
	v_mfma_f32_16x16x32_bf16 v[66:69], v[180:183], v[212:215], v[66:69]
	v_mfma_f32_16x16x32_bf16 v[122:125], v[176:179], v[192:195], v[122:125]
	v_mfma_f32_16x16x32_bf16 v[114:117], v[184:187], v[192:195], v[114:117]
	v_mfma_f32_16x16x32_bf16 v[106:109], v[176:179], v[200:203], v[106:109]
	v_mfma_f32_16x16x32_bf16 v[98:101], v[184:187], v[200:203], v[98:101]
	v_mfma_f32_16x16x32_bf16 v[90:93], v[176:179], v[208:211], v[90:93]
	v_mfma_f32_16x16x32_bf16 v[82:85], v[184:187], v[208:211], v[82:85]
	v_mfma_f32_16x16x32_bf16 v[74:77], v[176:179], v[216:219], v[74:77]
	v_mfma_f32_16x16x32_bf16 v[66:69], v[184:187], v[216:219], v[66:69]
	s_setprio 0
	s_barrier
	s_add_i32 s49, s39, s29
	v_lshl_add_u64 v[220:221], s[24:25], 0, v[136:137]
	s_mov_b32 m0, s49
	ds_read_b128 v[188:191], v156 offset:16384
	ds_read_b128 v[192:195], v156 offset:17408
	ds_read_b128 v[196:199], v156 offset:18432
	ds_read_b128 v[200:203], v156 offset:19456
	ds_read_b128 v[204:207], v156 offset:20480
	ds_read_b128 v[208:211], v156 offset:21504
	ds_read_b128 v[212:215], v156 offset:22528
	ds_read_b128 v[216:219], v156 offset:23552
	global_load_lds_dwordx4 v[220:221], off
	s_add_i32 m0, s49, 0x2000
	s_add_u32 s50, s24, 0x80000
	v_lshl_add_u64 v[222:223], s[24:25], 0, v[132:133]
	s_addc_u32 s51, s25, 0
	s_add_i32 s49, s40, s29
	global_load_lds_dwordx4 v[222:223], off
	v_lshl_add_u64 v[224:225], s[50:51], 0, v[136:137]
	s_mov_b32 m0, s49
	v_lshl_add_u64 v[226:227], s[26:27], 0, v[134:135]
	global_load_lds_dwordx4 v[224:225], off
	v_lshl_add_u64 v[224:225], s[50:51], 0, v[132:133]
	s_add_i32 m0, s49, 0x2000
	s_nop 0
	global_load_lds_dwordx4 v[224:225], off
	s_waitcnt vmcnt(6)
	s_waitcnt lgkmcnt(0)
	s_barrier
; #define PG8_STAGE(bufoff, gbase, voff) do { _Pragma("unroll") for (int _i = 0; _i < 2; ++_i) \
;         __builtin_amdgcn_global_load_lds((const unsigned*)((const char*)(gbase) + (voff)[_i]), (PG8_LAS unsigned*)(lds + (bufoff) + ldsw + _i * 8192), 16, 0, 0); } while (0)
; #define PG8_WAIT_V(n) asm volatile("s_waitcnt vmcnt(" #n ")" ::: "memory")
; #define PG8_WAIT_L(n) asm volatile("s_waitcnt lgkmcnt(" #n ")" ::: "memory")
; #define PG8_BAR __builtin_amdgcn_s_barrier()
; #define PG8_SCHED __builtin_amdgcn_sched_barrier(0)
; template <class Epi, class Sched, bool ALIGN_EPI = true, bool SP2 = true>
; __device__ __forceinline__ void gemm_phase(PG8_LAS unsigned char* lds, const int K  , const Sched& S, const Epi& E) {
;     ...
;             PG8_WAIT_V(8); PG8_WAIT_L(0); PG8_BAR; PG8_MMA(1, 0, At, B0); PG8_MMA(1, 1, At, B1); PG8_BAR; PG8_SCHED;
;             PG8_LDB(B0, 1, 0); PG8_LDB(B1, 1, 1); PG8_SCHED; PG8_LDA(At, 1, 0); PG8_STAGE(PG8_SA(0, 1), a2 + hstep, voffA);
;             PG8_WAIT_V(8); PG8_WAIT_L(0); PG8_BAR; PG8_MMA(0, 0, At, B0); PG8_MMA(0, 1, At, B1); PG8_BAR; PG8_SCHED;
	s_setprio 1
	s_waitcnt lgkmcnt(0)
	v_mfma_f32_16x16x32_bf16 v[62:65], v[148:151], v[188:191], v[62:65]
	v_mfma_f32_16x16x32_bf16 v[54:57], v[164:167], v[188:191], v[54:57]
	v_mfma_f32_16x16x32_bf16 v[46:49], v[148:151], v[196:199], v[46:49]
	v_mfma_f32_16x16x32_bf16 v[38:41], v[164:167], v[196:199], v[38:41]
	v_mfma_f32_16x16x32_bf16 v[30:33], v[148:151], v[204:207], v[30:33]
	v_mfma_f32_16x16x32_bf16 v[22:25], v[164:167], v[204:207], v[22:25]
	v_mfma_f32_16x16x32_bf16 v[14:17], v[148:151], v[212:215], v[14:17]
	v_mfma_f32_16x16x32_bf16 v[6:9], v[164:167], v[212:215], v[6:9]
	v_mfma_f32_16x16x32_bf16 v[62:65], v[160:163], v[192:195], v[62:65]
	v_mfma_f32_16x16x32_bf16 v[54:57], v[168:171], v[192:195], v[54:57]
	v_mfma_f32_16x16x32_bf16 v[46:49], v[160:163], v[200:203], v[46:49]
	v_mfma_f32_16x16x32_bf16 v[38:41], v[168:171], v[200:203], v[38:41]
	v_mfma_f32_16x16x32_bf16 v[30:33], v[160:163], v[208:211], v[30:33]
	v_mfma_f32_16x16x32_bf16 v[22:25], v[168:171], v[208:211], v[22:25]
	v_mfma_f32_16x16x32_bf16 v[14:17], v[160:163], v[216:219], v[14:17]
	v_mfma_f32_16x16x32_bf16 v[6:9], v[168:171], v[216:219], v[6:9]
	v_lshl_add_u64 v[224:225], s[26:27], 0, v[138:139]
	s_mov_b32 m0, s21
	s_nop 0
	global_load_lds_dwordx4 v[224:225], off
	s_mov_b32 m0, s31
	s_nop 0
	global_load_lds_dwordx4 v[226:227], off
	v_mfma_f32_16x16x32_bf16 v[58:61], v[172:175], v[188:191], v[58:61]
	v_mfma_f32_16x16x32_bf16 v[50:53], v[180:183], v[188:191], v[50:53]
	v_mfma_f32_16x16x32_bf16 v[42:45], v[172:175], v[196:199], v[42:45]
	v_mfma_f32_16x16x32_bf16 v[34:37], v[180:183], v[196:199], v[34:37]
	v_mfma_f32_16x16x32_bf16 v[26:29], v[172:175], v[204:207], v[26:29]
	v_mfma_f32_16x16x32_bf16 v[18:21], v[180:183], v[204:207], v[18:21]
	v_mfma_f32_16x16x32_bf16 v[10:13], v[172:175], v[212:215], v[10:13]
	v_mfma_f32_16x16x32_bf16 v[2:5], v[180:183], v[212:215], v[2:5]
	v_mfma_f32_16x16x32_bf16 v[58:61], v[176:179], v[192:195], v[58:61]
	v_mfma_f32_16x16x32_bf16 v[50:53], v[184:187], v[192:195], v[50:53]
	v_mfma_f32_16x16x32_bf16 v[42:45], v[176:179], v[200:203], v[42:45]
	v_mfma_f32_16x16x32_bf16 v[34:37], v[184:187], v[200:203], v[34:37]
	v_mfma_f32_16x16x32_bf16 v[26:29], v[176:179], v[208:211], v[26:29]
	v_mfma_f32_16x16x32_bf16 v[18:21], v[184:187], v[208:211], v[18:21]
	v_mfma_f32_16x16x32_bf16 v[10:13], v[176:179], v[216:219], v[10:13]
	v_mfma_f32_16x16x32_bf16 v[2:5], v[184:187], v[216:219], v[2:5]
	s_setprio 0
	s_barrier
	s_add_i32 s49, 0, 0x18000
	v_add_u32_e32 v159, s49, v152
	s_add_i32 s50, 0, 0x1c000
	ds_read_b128 v[148:151], v159
	ds_read_b128 v[160:163], v159 offset:1024
	ds_read_b128 v[164:167], v159 offset:2048
	ds_read_b128 v[168:171], v159 offset:3072
	v_add_u32_e32 v159, s50, v152
	ds_read_b128 v[172:175], v159
	ds_read_b128 v[176:179], v159 offset:1024
	ds_read_b128 v[180:183], v159 offset:2048
	ds_read_b128 v[184:187], v159 offset:3072
	s_add_u32 s26, s26, 0x80000
	s_addc_u32 s27, s27, 0
	s_mov_b32 m0, s33
	v_lshl_add_u64 v[230:231], s[26:27], 0, v[138:139]
	ds_read_b128 v[188:191], v156 offset:32768
	ds_read_b128 v[192:195], v156 offset:33792
	ds_read_b128 v[196:199], v156 offset:34816
	ds_read_b128 v[200:203], v156 offset:35840
	ds_read_b128 v[204:207], v156 offset:36864
	ds_read_b128 v[208:211], v156 offset:37888
	ds_read_b128 v[212:215], v156 offset:38912
	ds_read_b128 v[216:219], v156 offset:39936
	global_load_lds_dwordx4 v[230:231], off
	v_lshl_add_u64 v[230:231], s[26:27], 0, v[134:135]
	s_mov_b32 m0, s34
	s_nop 0
	global_load_lds_dwordx4 v[230:231], off
	s_waitcnt vmcnt(8)
	s_waitcnt lgkmcnt(0)
	s_barrier
	s_setprio 1
	s_waitcnt lgkmcnt(0)
	v_mfma_f32_16x16x32_bf16 v[126:129], v[148:151], v[188:191], v[126:129]
	v_mfma_f32_16x16x32_bf16 v[118:121], v[164:167], v[188:191], v[118:121]
	v_mfma_f32_16x16x32_bf16 v[110:113], v[148:151], v[196:199], v[110:113]
	v_mfma_f32_16x16x32_bf16 v[102:105], v[164:167], v[196:199], v[102:105]
	v_mfma_f32_16x16x32_bf16 v[94:97], v[148:151], v[204:207], v[94:97]
	v_mfma_f32_16x16x32_bf16 v[86:89], v[164:167], v[204:207], v[86:89]
	v_mfma_f32_16x16x32_bf16 v[78:81], v[148:151], v[212:215], v[78:81]
	v_mfma_f32_16x16x32_bf16 v[70:73], v[164:167], v[212:215], v[70:73]
	v_mfma_f32_16x16x32_bf16 v[126:129], v[160:163], v[192:195], v[126:129]
	v_mfma_f32_16x16x32_bf16 v[118:121], v[168:171], v[192:195], v[118:121]
	v_mfma_f32_16x16x32_bf16 v[110:113], v[160:163], v[200:203], v[110:113]
	v_mfma_f32_16x16x32_bf16 v[102:105], v[168:171], v[200:203], v[102:105]
	v_mfma_f32_16x16x32_bf16 v[94:97], v[160:163], v[208:211], v[94:97]
	v_mfma_f32_16x16x32_bf16 v[86:89], v[168:171], v[208:211], v[86:89]
	v_mfma_f32_16x16x32_bf16 v[78:81], v[160:163], v[216:219], v[78:81]
	v_mfma_f32_16x16x32_bf16 v[70:73], v[168:171], v[216:219], v[70:73]
	s_setprio 0
	s_setprio 1
	v_mfma_f32_16x16x32_bf16 v[122:125], v[172:175], v[188:191], v[122:125]
	v_mfma_f32_16x16x32_bf16 v[114:117], v[180:183], v[188:191], v[114:117]
	v_mfma_f32_16x16x32_bf16 v[106:109], v[172:175], v[196:199], v[106:109]
	v_mfma_f32_16x16x32_bf16 v[98:101], v[180:183], v[196:199], v[98:101]
	v_mfma_f32_16x16x32_bf16 v[90:93], v[172:175], v[204:207], v[90:93]
	v_mfma_f32_16x16x32_bf16 v[82:85], v[180:183], v[204:207], v[82:85]
	v_mfma_f32_16x16x32_bf16 v[74:77], v[172:175], v[212:215], v[74:77]
	v_mfma_f32_16x16x32_bf16 v[66:69], v[180:183], v[212:215], v[66:69]
	v_mfma_f32_16x16x32_bf16 v[122:125], v[176:179], v[192:195], v[122:125]
	v_mfma_f32_16x16x32_bf16 v[114:117], v[184:187], v[192:195], v[114:117]
	v_mfma_f32_16x16x32_bf16 v[106:109], v[176:179], v[200:203], v[106:109]
	v_mfma_f32_16x16x32_bf16 v[98:101], v[184:187], v[200:203], v[98:101]
	v_mfma_f32_16x16x32_bf16 v[90:93], v[176:179], v[208:211], v[90:93]
	v_mfma_f32_16x16x32_bf16 v[82:85], v[184:187], v[208:211], v[82:85]
	v_mfma_f32_16x16x32_bf16 v[74:77], v[176:179], v[216:219], v[74:77]
	v_mfma_f32_16x16x32_bf16 v[66:69], v[184:187], v[216:219], v[66:69]
	s_setprio 0
	s_barrier
; #define PG8_STAGE(bufoff, gbase, voff) do { _Pragma("unroll") for (int _i = 0; _i < 2; ++_i) \
;         __builtin_amdgcn_global_load_lds((const unsigned*)((const char*)(gbase) + (voff)[_i]), (PG8_LAS unsigned*)(lds + (bufoff) + ldsw + _i * 8192), 16, 0, 0); } while (0)
; #define PG8_WAIT_V(n) asm volatile("s_waitcnt vmcnt(" #n ")" ::: "memory")
; #define PG8_WAIT_L(n) asm volatile("s_waitcnt lgkmcnt(" #n ")" ::: "memory")
; #define PG8_BAR __builtin_amdgcn_s_barrier()
; #define PG8_SCHED __builtin_amdgcn_sched_barrier(0)
; template <class Epi, class Sched, bool ALIGN_EPI = true, bool SP2 = true>
; __device__ __forceinline__ void gemm_phase(PG8_LAS unsigned char* lds, const int K  , const Sched& S, const Epi& E) {
;     ...
;             PG8_LDA(At, 1, 1); PG8_STAGE(PG8_SB(1, 0), b3, voffB); PG8_STAGE(PG8_SB(1, 1), b3 + hstep, voffB); PG8_STAGE(PG8_SA(1, 0), a3, voffA);
;             PG8_WAIT_V(8); PG8_WAIT_L(0); PG8_BAR; PG8_MMA(1, 0, At, B0); PG8_MMA(1, 1, At, B1); PG8_BAR; PG8_SCHED;
;     ...
;         if constexpr (ALIGN_EPI) { if (wr == 0) PG8_BAR; }
	s_add_i32 s26, s49, s29
	v_lshl_add_u64 v[220:221], v[220:221], 0, s[4:5]
	s_mov_b32 m0, s26
	ds_read_b128 v[188:191], v156 offset:49152
	ds_read_b128 v[192:195], v156 offset:50176
	ds_read_b128 v[196:199], v156 offset:51200
	ds_read_b128 v[200:203], v156 offset:52224
	ds_read_b128 v[204:207], v156 offset:53248
	ds_read_b128 v[208:211], v156 offset:54272
	ds_read_b128 v[212:215], v156 offset:55296
	ds_read_b128 v[216:219], v156 offset:56320
	global_load_lds_dwordx4 v[220:221], off
	s_add_i32 m0, s26, 0x2000
	s_add_u32 s24, s24, 0x80080
	v_lshl_add_u64 v[220:221], v[222:223], 0, s[4:5]
	s_addc_u32 s25, s25, 0
	s_add_i32 s26, s50, s29
	global_load_lds_dwordx4 v[220:221], off
	v_lshl_add_u64 v[220:221], s[24:25], 0, v[136:137]
	s_mov_b32 m0, s26
	s_nop 0
	global_load_lds_dwordx4 v[220:221], off
	v_lshl_add_u64 v[220:221], s[24:25], 0, v[132:133]
	s_add_i32 m0, s26, 0x2000
	s_nop 0
	global_load_lds_dwordx4 v[220:221], off
	s_waitcnt vmcnt(6)
	s_waitcnt lgkmcnt(0)
	s_barrier
	s_setprio 1
	s_waitcnt lgkmcnt(0)
	v_mfma_f32_16x16x32_bf16 v[62:65], v[148:151], v[188:191], v[62:65]
	v_mfma_f32_16x16x32_bf16 v[54:57], v[164:167], v[188:191], v[54:57]
	v_mfma_f32_16x16x32_bf16 v[46:49], v[148:151], v[196:199], v[46:49]
	v_mfma_f32_16x16x32_bf16 v[38:41], v[164:167], v[196:199], v[38:41]
	v_mfma_f32_16x16x32_bf16 v[30:33], v[148:151], v[204:207], v[30:33]
	v_mfma_f32_16x16x32_bf16 v[22:25], v[164:167], v[204:207], v[22:25]
	v_mfma_f32_16x16x32_bf16 v[14:17], v[148:151], v[212:215], v[14:17]
	v_mfma_f32_16x16x32_bf16 v[6:9], v[164:167], v[212:215], v[6:9]
	v_mfma_f32_16x16x32_bf16 v[62:65], v[160:163], v[192:195], v[62:65]
	v_mfma_f32_16x16x32_bf16 v[54:57], v[168:171], v[192:195], v[54:57]
	v_mfma_f32_16x16x32_bf16 v[46:49], v[160:163], v[200:203], v[46:49]
	v_mfma_f32_16x16x32_bf16 v[38:41], v[168:171], v[200:203], v[38:41]
	v_mfma_f32_16x16x32_bf16 v[30:33], v[160:163], v[208:211], v[30:33]
	v_mfma_f32_16x16x32_bf16 v[22:25], v[168:171], v[208:211], v[22:25]
	v_mfma_f32_16x16x32_bf16 v[14:17], v[160:163], v[216:219], v[14:17]
	v_mfma_f32_16x16x32_bf16 v[6:9], v[168:171], v[216:219], v[6:9]
	v_lshl_add_u64 v[220:221], v[224:225], 0, s[4:5]
	s_mov_b32 m0, s36
	s_nop 0
	global_load_lds_dwordx4 v[220:221], off
	v_lshl_add_u64 v[220:221], v[226:227], 0, s[4:5]
	s_mov_b32 m0, s37
	s_nop 0
	global_load_lds_dwordx4 v[220:221], off
	v_mfma_f32_16x16x32_bf16 v[58:61], v[172:175], v[188:191], v[58:61]
	v_mfma_f32_16x16x32_bf16 v[50:53], v[180:183], v[188:191], v[50:53]
	v_mfma_f32_16x16x32_bf16 v[42:45], v[172:175], v[196:199], v[42:45]
	v_mfma_f32_16x16x32_bf16 v[34:37], v[180:183], v[196:199], v[34:37]
	v_mfma_f32_16x16x32_bf16 v[26:29], v[172:175], v[204:207], v[26:29]
	v_mfma_f32_16x16x32_bf16 v[18:21], v[180:183], v[204:207], v[18:21]
	v_mfma_f32_16x16x32_bf16 v[10:13], v[172:175], v[212:215], v[10:13]
	v_mfma_f32_16x16x32_bf16 v[2:5], v[180:183], v[212:215], v[2:5]
	v_mfma_f32_16x16x32_bf16 v[58:61], v[176:179], v[192:195], v[58:61]
	v_mfma_f32_16x16x32_bf16 v[50:53], v[184:187], v[192:195], v[50:53]
	v_mfma_f32_16x16x32_bf16 v[42:45], v[176:179], v[200:203], v[42:45]
	v_mfma_f32_16x16x32_bf16 v[34:37], v[184:187], v[200:203], v[34:37]
	v_mfma_f32_16x16x32_bf16 v[26:29], v[176:179], v[208:211], v[26:29]
	v_mfma_f32_16x16x32_bf16 v[18:21], v[184:187], v[208:211], v[18:21]
	v_mfma_f32_16x16x32_bf16 v[10:13], v[176:179], v[216:219], v[10:13]
	v_mfma_f32_16x16x32_bf16 v[2:5], v[184:187], v[216:219], v[2:5]
	s_setprio 0
	s_barrier
	s_add_i32 s48, s48, 2
	s_add_u32 s22, s22, 0x100
	s_addc_u32 s23, s23, 0
	s_add_u32 s46, s46, 0x100
	s_addc_u32 s47, s47, 0
	s_cmp_gt_u32 s48, 29
	s_cbranch_scc0 .LBB0_1099
	s_and_b64 vcc, exec, s[8:9]
	s_cbranch_vccz .LBB0_1102
	s_barrier

; #define PG8_STAGE(bufoff, gbase, voff) do { _Pragma("unroll") for (int _i = 0; _i < 2; ++_i) \
;         __builtin_amdgcn_global_load_lds((const unsigned*)((const char*)(gbase) + (voff)[_i]), (PG8_LAS unsigned*)(lds + (bufoff) + ldsw + _i * 8192), 16, 0, 0); } while (0)
; #define PG8_WAIT_V(n) asm volatile("s_waitcnt vmcnt(" #n ")" ::: "memory")
; #define PG8_WAIT_L(n) asm volatile("s_waitcnt lgkmcnt(" #n ")" ::: "memory")
; #define PG8_BAR __builtin_amdgcn_s_barrier()
; #define PG8_SCHED __builtin_amdgcn_sched_barrier(0)
;     __device__ __forceinline__ int nt(const pg8::Unit& u) const { return u.kind == 0 ? ntiles : q_nt(u.kind - 1); }
; template <class Epi, class Sched, bool ALIGN_EPI = true, bool SP2 = true>
; __device__ __forceinline__ void gemm_phase(PG8_LAS unsigned char* lds, const int K  , const Sched& S, const Epi& E) {
;     ...
;             const bool last = (t == nt - 2);
;             const char* a1 = cA + (size_t)(t + 1) * kstep;
;             const char* a2 = last ? nA : cA + (size_t)(t + 2) * kstep; const char* b2 = last ? nB : cB + (size_t)(t + 2) * kstep;
;             const char* a3 = a2 + kstep; const char* b3 = b2 + kstep;
;     ...
;             PG8_LDB(B0, 0, 0); PG8_LDB(B1, 0, 1); PG8_SCHED; PG8_LDA(At, 0, 0); PG8_STAGE(PG8_SA(1, 1), a1 + hstep, voffA);
;             PG8_WAIT_V(8); PG8_WAIT_L(0); PG8_BAR; PG8_MMA(0, 0, At, B0); PG8_MMA(0, 1, At, B1); PG8_BAR; PG8_SCHED;
;             PG8_LDA(At, 0, 1); PG8_STAGE(PG8_SB(0, 0), b2, voffB); PG8_STAGE(PG8_SB(0, 1), b2 + hstep, voffB); PG8_STAGE(PG8_SA(0, 0), a2, voffA);
.LBB0_1448:
	ds_read_b128 v[148:151], v154
	ds_read_b128 v[160:163], v154 offset:1024
	ds_read_b128 v[164:167], v154 offset:2048
	ds_read_b128 v[168:171], v154 offset:3072
	ds_read_b128 v[172:175], v155
	ds_read_b128 v[176:179], v155 offset:1024
	ds_read_b128 v[180:183], v155 offset:2048
	ds_read_b128 v[184:187], v155 offset:3072
	s_add_u32 s26, s24, 0xfff80080
	s_addc_u32 s27, s25, -1
	s_cmp_eq_u32 s50, 28
	s_cselect_b32 s29, s17, s27
	s_cselect_b32 s28, s46, s26
	s_cselect_b32 s27, s11, s49
	s_cselect_b32 s26, s47, s48
	v_lshl_add_u64 v[220:221], s[24:25], 0, v[140:141]
	s_add_i32 m0, s23, 0xc000
	ds_read_b128 v[188:191], v156
	ds_read_b128 v[192:195], v156 offset:1024
	ds_read_b128 v[196:199], v156 offset:2048
	ds_read_b128 v[200:203], v156 offset:3072
	ds_read_b128 v[204:207], v156 offset:4096
	ds_read_b128 v[208:211], v156 offset:5120
	ds_read_b128 v[212:215], v156 offset:6144
	ds_read_b128 v[216:219], v156 offset:7168
	global_load_lds_dwordx4 v[220:221], off
	v_lshl_add_u64 v[220:221], s[24:25], 0, v[142:143]
	s_add_i32 m0, s23, 0xe000
	s_nop 0
	global_load_lds_dwordx4 v[220:221], off
	s_waitcnt vmcnt(8)
	s_waitcnt lgkmcnt(0)
	s_barrier
	s_setprio 1
	s_waitcnt lgkmcnt(0)
	v_mfma_f32_16x16x32_bf16 v[126:129], v[148:151], v[188:191], v[126:129]
	v_mfma_f32_16x16x32_bf16 v[118:121], v[164:167], v[188:191], v[118:121]
	v_mfma_f32_16x16x32_bf16 v[110:113], v[148:151], v[196:199], v[110:113]
	v_mfma_f32_16x16x32_bf16 v[102:105], v[164:167], v[196:199], v[102:105]
	v_mfma_f32_16x16x32_bf16 v[94:97], v[148:151], v[204:207], v[94:97]
	v_mfma_f32_16x16x32_bf16 v[86:89], v[164:167], v[204:207], v[86:89]
	v_mfma_f32_16x16x32_bf16 v[78:81], v[148:151], v[212:215], v[78:81]
	v_mfma_f32_16x16x32_bf16 v[70:73], v[164:167], v[212:215], v[70:73]
	v_mfma_f32_16x16x32_bf16 v[126:129], v[160:163], v[192:195], v[126:129]
	v_mfma_f32_16x16x32_bf16 v[118:121], v[168:171], v[192:195], v[118:121]
	v_mfma_f32_16x16x32_bf16 v[110:113], v[160:163], v[200:203], v[110:113]
	v_mfma_f32_16x16x32_bf16 v[102:105], v[168:171], v[200:203], v[102:105]
	v_mfma_f32_16x16x32_bf16 v[94:97], v[160:163], v[208:211], v[94:97]
	v_mfma_f32_16x16x32_bf16 v[86:89], v[168:171], v[208:211], v[86:89]
	v_mfma_f32_16x16x32_bf16 v[78:81], v[160:163], v[216:219], v[78:81]
	v_mfma_f32_16x16x32_bf16 v[70:73], v[168:171], v[216:219], v[70:73]
	s_setprio 0
	s_setprio 1
	v_mfma_f32_16x16x32_bf16 v[122:125], v[172:175], v[188:191], v[122:125]
	v_mfma_f32_16x16x32_bf16 v[114:117], v[180:183], v[188:191], v[114:117]
	v_mfma_f32_16x16x32_bf16 v[106:109], v[172:175], v[196:199], v[106:109]
	v_mfma_f32_16x16x32_bf16 v[98:101], v[180:183], v[196:199], v[98:101]
	v_mfma_f32_16x16x32_bf16 v[90:93], v[172:175], v[204:207], v[90:93]
	v_mfma_f32_16x16x32_bf16 v[82:85], v[180:183], v[204:207], v[82:85]
	v_mfma_f32_16x16x32_bf16 v[74:77], v[172:175], v[212:215], v[74:77]
	v_mfma_f32_16x16x32_bf16 v[66:69], v[180:183], v[212:215], v[66:69]
	v_mfma_f32_16x16x32_bf16 v[122:125], v[176:179], v[192:195], v[122:125]
	v_mfma_f32_16x16x32_bf16 v[114:117], v[184:187], v[192:195], v[114:117]
	v_mfma_f32_16x16x32_bf16 v[106:109], v[176:179], v[200:203], v[106:109]
	v_mfma_f32_16x16x32_bf16 v[98:101], v[184:187], v[200:203], v[98:101]
	v_mfma_f32_16x16x32_bf16 v[90:93], v[176:179], v[208:211], v[90:93]
	v_mfma_f32_16x16x32_bf16 v[82:85], v[184:187], v[208:211], v[82:85]
	v_mfma_f32_16x16x32_bf16 v[74:77], v[176:179], v[216:219], v[74:77]
	v_mfma_f32_16x16x32_bf16 v[66:69], v[184:187], v[216:219], v[66:69]
	s_setprio 0
	s_barrier
	s_add_i32 s51, s41, s31
	v_lshl_add_u64 v[220:221], s[26:27], 0, v[136:137]
	s_mov_b32 m0, s51
	ds_read_b128 v[188:191], v156 offset:16384
	ds_read_b128 v[192:195], v156 offset:17408
	ds_read_b128 v[196:199], v156 offset:18432
	ds_read_b128 v[200:203], v156 offset:19456
	ds_read_b128 v[204:207], v156 offset:20480
	ds_read_b128 v[208:211], v156 offset:21504
	ds_read_b128 v[212:215], v156 offset:22528
	ds_read_b128 v[216:219], v156 offset:23552
	global_load_lds_dwordx4 v[220:221], off
	s_add_i32 m0, s51, 0x2000
	s_add_u32 s68, s26, 0x80000
	v_lshl_add_u64 v[222:223], s[26:27], 0, v[132:133]
	s_addc_u32 s69, s27, 0
	s_add_i32 s51, s42, s31
	global_load_lds_dwordx4 v[222:223], off
	v_lshl_add_u64 v[224:225], s[68:69], 0, v[136:137]
	s_mov_b32 m0, s51
	v_lshl_add_u64 v[226:227], s[28:29], 0, v[134:135]
	global_load_lds_dwordx4 v[224:225], off
	v_lshl_add_u64 v[224:225], s[68:69], 0, v[132:133]
	s_add_i32 m0, s51, 0x2000
	s_nop 0
	global_load_lds_dwordx4 v[224:225], off
	s_waitcnt vmcnt(6)
	s_waitcnt lgkmcnt(0)
	s_barrier
; #define PG8_STAGE(bufoff, gbase, voff) do { _Pragma("unroll") for (int _i = 0; _i < 2; ++_i) \
;         __builtin_amdgcn_global_load_lds((const unsigned*)((const char*)(gbase) + (voff)[_i]), (PG8_LAS unsigned*)(lds + (bufoff) + ldsw + _i * 8192), 16, 0, 0); } while (0)
; #define PG8_WAIT_V(n) asm volatile("s_waitcnt vmcnt(" #n ")" ::: "memory")
; #define PG8_WAIT_L(n) asm volatile("s_waitcnt lgkmcnt(" #n ")" ::: "memory")
; #define PG8_BAR __builtin_amdgcn_s_barrier()
; #define PG8_SCHED __builtin_amdgcn_sched_barrier(0)
; template <class Epi, class Sched, bool ALIGN_EPI = true, bool SP2 = true>
; __device__ __forceinline__ void gemm_phase(PG8_LAS unsigned char* lds, const int K  , const Sched& S, const Epi& E) {
;     ...
;             PG8_LDA(At, 0, 1); PG8_STAGE(PG8_SB(0, 0), b2, voffB); PG8_STAGE(PG8_SB(0, 1), b2 + hstep, voffB); PG8_STAGE(PG8_SA(0, 0), a2, voffA);
;             PG8_WAIT_V(8); PG8_WAIT_L(0); PG8_BAR; PG8_MMA(1, 0, At, B0); PG8_MMA(1, 1, At, B1); PG8_BAR; PG8_SCHED;
;             PG8_LDB(B0, 1, 0); PG8_LDB(B1, 1, 1); PG8_SCHED; PG8_LDA(At, 1, 0); PG8_STAGE(PG8_SA(0, 1), a2 + hstep, voffA);
;             PG8_WAIT_V(8); PG8_WAIT_L(0); PG8_BAR; PG8_MMA(0, 0, At, B0); PG8_MMA(0, 1, At, B1); PG8_BAR; PG8_SCHED;
	s_setprio 1
	s_waitcnt lgkmcnt(0)
	v_mfma_f32_16x16x32_bf16 v[62:65], v[148:151], v[188:191], v[62:65]
	v_mfma_f32_16x16x32_bf16 v[54:57], v[164:167], v[188:191], v[54:57]
	v_mfma_f32_16x16x32_bf16 v[46:49], v[148:151], v[196:199], v[46:49]
	v_mfma_f32_16x16x32_bf16 v[38:41], v[164:167], v[196:199], v[38:41]
	v_mfma_f32_16x16x32_bf16 v[30:33], v[148:151], v[204:207], v[30:33]
	v_mfma_f32_16x16x32_bf16 v[22:25], v[164:167], v[204:207], v[22:25]
	v_mfma_f32_16x16x32_bf16 v[14:17], v[148:151], v[212:215], v[14:17]
	v_mfma_f32_16x16x32_bf16 v[6:9], v[164:167], v[212:215], v[6:9]
	v_mfma_f32_16x16x32_bf16 v[62:65], v[160:163], v[192:195], v[62:65]
	v_mfma_f32_16x16x32_bf16 v[54:57], v[168:171], v[192:195], v[54:57]
	v_mfma_f32_16x16x32_bf16 v[46:49], v[160:163], v[200:203], v[46:49]
	v_mfma_f32_16x16x32_bf16 v[38:41], v[168:171], v[200:203], v[38:41]
	v_mfma_f32_16x16x32_bf16 v[30:33], v[160:163], v[208:211], v[30:33]
	v_mfma_f32_16x16x32_bf16 v[22:25], v[168:171], v[208:211], v[22:25]
	v_mfma_f32_16x16x32_bf16 v[14:17], v[160:163], v[216:219], v[14:17]
	v_mfma_f32_16x16x32_bf16 v[6:9], v[168:171], v[216:219], v[6:9]
	v_lshl_add_u64 v[224:225], s[28:29], 0, v[138:139]
	s_mov_b32 m0, s23
	s_nop 0
	global_load_lds_dwordx4 v[224:225], off
	s_mov_b32 m0, s34
	s_nop 0
	global_load_lds_dwordx4 v[226:227], off
	v_mfma_f32_16x16x32_bf16 v[58:61], v[172:175], v[188:191], v[58:61]
	v_mfma_f32_16x16x32_bf16 v[50:53], v[180:183], v[188:191], v[50:53]
	v_mfma_f32_16x16x32_bf16 v[42:45], v[172:175], v[196:199], v[42:45]
	v_mfma_f32_16x16x32_bf16 v[34:37], v[180:183], v[196:199], v[34:37]
	v_mfma_f32_16x16x32_bf16 v[26:29], v[172:175], v[204:207], v[26:29]
	v_mfma_f32_16x16x32_bf16 v[18:21], v[180:183], v[204:207], v[18:21]
	v_mfma_f32_16x16x32_bf16 v[10:13], v[172:175], v[212:215], v[10:13]
	v_mfma_f32_16x16x32_bf16 v[2:5], v[180:183], v[212:215], v[2:5]
	v_mfma_f32_16x16x32_bf16 v[58:61], v[176:179], v[192:195], v[58:61]
	v_mfma_f32_16x16x32_bf16 v[50:53], v[184:187], v[192:195], v[50:53]
	v_mfma_f32_16x16x32_bf16 v[42:45], v[176:179], v[200:203], v[42:45]
	v_mfma_f32_16x16x32_bf16 v[34:37], v[184:187], v[200:203], v[34:37]
	v_mfma_f32_16x16x32_bf16 v[26:29], v[176:179], v[208:211], v[26:29]
	v_mfma_f32_16x16x32_bf16 v[18:21], v[184:187], v[208:211], v[18:21]
	v_mfma_f32_16x16x32_bf16 v[10:13], v[176:179], v[216:219], v[10:13]
	v_mfma_f32_16x16x32_bf16 v[2:5], v[184:187], v[216:219], v[2:5]
	s_setprio 0
	s_barrier
	s_add_i32 s51, 0, 0x18000
	v_add_u32_e32 v159, s51, v152
	s_add_i32 s68, 0, 0x1c000
	ds_read_b128 v[148:151], v159
	ds_read_b128 v[160:163], v159 offset:1024
	ds_read_b128 v[164:167], v159 offset:2048
	ds_read_b128 v[168:171], v159 offset:3072
	v_add_u32_e32 v159, s68, v152
	ds_read_b128 v[172:175], v159
	ds_read_b128 v[176:179], v159 offset:1024
	ds_read_b128 v[180:183], v159 offset:2048
	ds_read_b128 v[184:187], v159 offset:3072
	s_add_u32 s28, s28, 0x80000
	s_addc_u32 s29, s29, 0
	s_mov_b32 m0, s35
	v_lshl_add_u64 v[230:231], s[28:29], 0, v[138:139]
	ds_read_b128 v[188:191], v156 offset:32768
	ds_read_b128 v[192:195], v156 offset:33792
	ds_read_b128 v[196:199], v156 offset:34816
	ds_read_b128 v[200:203], v156 offset:35840
	ds_read_b128 v[204:207], v156 offset:36864
	ds_read_b128 v[208:211], v156 offset:37888
	ds_read_b128 v[212:215], v156 offset:38912
	ds_read_b128 v[216:219], v156 offset:39936
	global_load_lds_dwordx4 v[230:231], off
	v_lshl_add_u64 v[230:231], s[28:29], 0, v[134:135]
	s_mov_b32 m0, s36
	s_nop 0
	global_load_lds_dwordx4 v[230:231], off
	s_waitcnt vmcnt(8)
	s_waitcnt lgkmcnt(0)
	s_barrier
	s_setprio 1
	s_waitcnt lgkmcnt(0)
	v_mfma_f32_16x16x32_bf16 v[126:129], v[148:151], v[188:191], v[126:129]
	v_mfma_f32_16x16x32_bf16 v[118:121], v[164:167], v[188:191], v[118:121]
	v_mfma_f32_16x16x32_bf16 v[110:113], v[148:151], v[196:199], v[110:113]
	v_mfma_f32_16x16x32_bf16 v[102:105], v[164:167], v[196:199], v[102:105]
	v_mfma_f32_16x16x32_bf16 v[94:97], v[148:151], v[204:207], v[94:97]
	v_mfma_f32_16x16x32_bf16 v[86:89], v[164:167], v[204:207], v[86:89]
	v_mfma_f32_16x16x32_bf16 v[78:81], v[148:151], v[212:215], v[78:81]
	v_mfma_f32_16x16x32_bf16 v[70:73], v[164:167], v[212:215], v[70:73]
	v_mfma_f32_16x16x32_bf16 v[126:129], v[160:163], v[192:195], v[126:129]
	v_mfma_f32_16x16x32_bf16 v[118:121], v[168:171], v[192:195], v[118:121]
	v_mfma_f32_16x16x32_bf16 v[110:113], v[160:163], v[200:203], v[110:113]
	v_mfma_f32_16x16x32_bf16 v[102:105], v[168:171], v[200:203], v[102:105]
	v_mfma_f32_16x16x32_bf16 v[94:97], v[160:163], v[208:211], v[94:97]
	v_mfma_f32_16x16x32_bf16 v[86:89], v[168:171], v[208:211], v[86:89]
	v_mfma_f32_16x16x32_bf16 v[78:81], v[160:163], v[216:219], v[78:81]
	v_mfma_f32_16x16x32_bf16 v[70:73], v[168:171], v[216:219], v[70:73]
	s_setprio 0
	s_setprio 1
	v_mfma_f32_16x16x32_bf16 v[122:125], v[172:175], v[188:191], v[122:125]
	v_mfma_f32_16x16x32_bf16 v[114:117], v[180:183], v[188:191], v[114:117]
	v_mfma_f32_16x16x32_bf16 v[106:109], v[172:175], v[196:199], v[106:109]
	v_mfma_f32_16x16x32_bf16 v[98:101], v[180:183], v[196:199], v[98:101]
	v_mfma_f32_16x16x32_bf16 v[90:93], v[172:175], v[204:207], v[90:93]
	v_mfma_f32_16x16x32_bf16 v[82:85], v[180:183], v[204:207], v[82:85]
	v_mfma_f32_16x16x32_bf16 v[74:77], v[172:175], v[212:215], v[74:77]
	v_mfma_f32_16x16x32_bf16 v[66:69], v[180:183], v[212:215], v[66:69]
	v_mfma_f32_16x16x32_bf16 v[122:125], v[176:179], v[192:195], v[122:125]
	v_mfma_f32_16x16x32_bf16 v[114:117], v[184:187], v[192:195], v[114:117]
	v_mfma_f32_16x16x32_bf16 v[106:109], v[176:179], v[200:203], v[106:109]
	v_mfma_f32_16x16x32_bf16 v[98:101], v[184:187], v[200:203], v[98:101]
	v_mfma_f32_16x16x32_bf16 v[90:93], v[176:179], v[208:211], v[90:93]
	v_mfma_f32_16x16x32_bf16 v[82:85], v[184:187], v[208:211], v[82:85]
	v_mfma_f32_16x16x32_bf16 v[74:77], v[176:179], v[216:219], v[74:77]
	v_mfma_f32_16x16x32_bf16 v[66:69], v[184:187], v[216:219], v[66:69]
	s_setprio 0
	s_barrier
; #define PG8_STAGE(bufoff, gbase, voff) do { _Pragma("unroll") for (int _i = 0; _i < 2; ++_i) \
;         __builtin_amdgcn_global_load_lds((const unsigned*)((const char*)(gbase) + (voff)[_i]), (PG8_LAS unsigned*)(lds + (bufoff) + ldsw + _i * 8192), 16, 0, 0); } while (0)
; #define PG8_WAIT_V(n) asm volatile("s_waitcnt vmcnt(" #n ")" ::: "memory")
; #define PG8_WAIT_L(n) asm volatile("s_waitcnt lgkmcnt(" #n ")" ::: "memory")
; #define PG8_BAR __builtin_amdgcn_s_barrier()
; #define PG8_SCHED __builtin_amdgcn_sched_barrier(0)
; template <class Epi, class Sched, bool ALIGN_EPI = true, bool SP2 = true>
; __device__ __forceinline__ void gemm_phase(PG8_LAS unsigned char* lds, const int K  , const Sched& S, const Epi& E) {
;     ...
;             PG8_LDA(At, 1, 1); PG8_STAGE(PG8_SB(1, 0), b3, voffB); PG8_STAGE(PG8_SB(1, 1), b3 + hstep, voffB); PG8_STAGE(PG8_SA(1, 0), a3, voffA);
;             PG8_WAIT_V(8); PG8_WAIT_L(0); PG8_BAR; PG8_MMA(1, 0, At, B0); PG8_MMA(1, 1, At, B1); PG8_BAR; PG8_SCHED;
;     ...
;         if constexpr (ALIGN_EPI) { if (wr == 0) PG8_BAR; }
	s_add_i32 s28, s51, s31
	v_lshl_add_u64 v[220:221], v[220:221], 0, s[4:5]
	s_mov_b32 m0, s28
	ds_read_b128 v[188:191], v156 offset:49152
	ds_read_b128 v[192:195], v156 offset:50176
	ds_read_b128 v[196:199], v156 offset:51200
	ds_read_b128 v[200:203], v156 offset:52224
	ds_read_b128 v[204:207], v156 offset:53248
	ds_read_b128 v[208:211], v156 offset:54272
	ds_read_b128 v[212:215], v156 offset:55296
	ds_read_b128 v[216:219], v156 offset:56320
	global_load_lds_dwordx4 v[220:221], off
	s_add_i32 m0, s28, 0x2000
	s_add_u32 s26, s26, 0x80080
	v_lshl_add_u64 v[220:221], v[222:223], 0, s[4:5]
	s_addc_u32 s27, s27, 0
	s_add_i32 s28, s68, s31
	global_load_lds_dwordx4 v[220:221], off
	v_lshl_add_u64 v[220:221], s[26:27], 0, v[136:137]
	s_mov_b32 m0, s28
	s_nop 0
	global_load_lds_dwordx4 v[220:221], off
	v_lshl_add_u64 v[220:221], s[26:27], 0, v[132:133]
	s_add_i32 m0, s28, 0x2000
	s_nop 0
	global_load_lds_dwordx4 v[220:221], off
	s_waitcnt vmcnt(6)
	s_waitcnt lgkmcnt(0)
	s_barrier
	s_setprio 1
	s_waitcnt lgkmcnt(0)
	v_mfma_f32_16x16x32_bf16 v[62:65], v[148:151], v[188:191], v[62:65]
	v_mfma_f32_16x16x32_bf16 v[54:57], v[164:167], v[188:191], v[54:57]
	v_mfma_f32_16x16x32_bf16 v[46:49], v[148:151], v[196:199], v[46:49]
	v_mfma_f32_16x16x32_bf16 v[38:41], v[164:167], v[196:199], v[38:41]
	v_mfma_f32_16x16x32_bf16 v[30:33], v[148:151], v[204:207], v[30:33]
	v_mfma_f32_16x16x32_bf16 v[22:25], v[164:167], v[204:207], v[22:25]
	v_mfma_f32_16x16x32_bf16 v[14:17], v[148:151], v[212:215], v[14:17]
	v_mfma_f32_16x16x32_bf16 v[6:9], v[164:167], v[212:215], v[6:9]
	v_mfma_f32_16x16x32_bf16 v[62:65], v[160:163], v[192:195], v[62:65]
	v_mfma_f32_16x16x32_bf16 v[54:57], v[168:171], v[192:195], v[54:57]
	v_mfma_f32_16x16x32_bf16 v[46:49], v[160:163], v[200:203], v[46:49]
	v_mfma_f32_16x16x32_bf16 v[38:41], v[168:171], v[200:203], v[38:41]
	v_mfma_f32_16x16x32_bf16 v[30:33], v[160:163], v[208:211], v[30:33]
	v_mfma_f32_16x16x32_bf16 v[22:25], v[168:171], v[208:211], v[22:25]
	v_mfma_f32_16x16x32_bf16 v[14:17], v[160:163], v[216:219], v[14:17]
	v_mfma_f32_16x16x32_bf16 v[6:9], v[168:171], v[216:219], v[6:9]
	v_lshl_add_u64 v[220:221], v[224:225], 0, s[4:5]
	s_mov_b32 m0, s38
	s_nop 0
	global_load_lds_dwordx4 v[220:221], off
	v_lshl_add_u64 v[220:221], v[226:227], 0, s[4:5]
	s_mov_b32 m0, s39
	s_nop 0
	global_load_lds_dwordx4 v[220:221], off
	v_mfma_f32_16x16x32_bf16 v[58:61], v[172:175], v[188:191], v[58:61]
	v_mfma_f32_16x16x32_bf16 v[50:53], v[180:183], v[188:191], v[50:53]
	v_mfma_f32_16x16x32_bf16 v[42:45], v[172:175], v[196:199], v[42:45]
	v_mfma_f32_16x16x32_bf16 v[34:37], v[180:183], v[196:199], v[34:37]
	v_mfma_f32_16x16x32_bf16 v[26:29], v[172:175], v[204:207], v[26:29]
	v_mfma_f32_16x16x32_bf16 v[18:21], v[180:183], v[204:207], v[18:21]
	v_mfma_f32_16x16x32_bf16 v[10:13], v[172:175], v[212:215], v[10:13]
	v_mfma_f32_16x16x32_bf16 v[2:5], v[180:183], v[212:215], v[2:5]
	v_mfma_f32_16x16x32_bf16 v[58:61], v[176:179], v[192:195], v[58:61]
	v_mfma_f32_16x16x32_bf16 v[50:53], v[184:187], v[192:195], v[50:53]
	v_mfma_f32_16x16x32_bf16 v[42:45], v[176:179], v[200:203], v[42:45]
	v_mfma_f32_16x16x32_bf16 v[34:37], v[184:187], v[200:203], v[34:37]
	v_mfma_f32_16x16x32_bf16 v[26:29], v[176:179], v[208:211], v[26:29]
	v_mfma_f32_16x16x32_bf16 v[18:21], v[184:187], v[208:211], v[18:21]
	v_mfma_f32_16x16x32_bf16 v[10:13], v[176:179], v[216:219], v[10:13]
	v_mfma_f32_16x16x32_bf16 v[2:5], v[184:187], v[216:219], v[2:5]
	s_setprio 0
	s_barrier
	s_add_i32 s50, s50, 2
	s_add_u32 s24, s24, 0x100
	s_addc_u32 s25, s25, 0
	s_add_u32 s48, s48, 0x100
	s_addc_u32 s49, s49, 0
	s_cmp_gt_u32 s50, 29
	s_cbranch_scc0 .LBB0_1448
	s_and_b64 vcc, exec, s[8:9]
	s_cbranch_vccz .LBB0_1451
	s_barrier

; #define PG8_STAGE(bufoff, gbase, voff) do { _Pragma("unroll") for (int _i = 0; _i < 2; ++_i) \
;         __builtin_amdgcn_global_load_lds((const unsigned*)((const char*)(gbase) + (voff)[_i]), (PG8_LAS unsigned*)(lds + (bufoff) + ldsw + _i * 8192), 16, 0, 0); } while (0)
; #define PG8_WAIT_V(n) asm volatile("s_waitcnt vmcnt(" #n ")" ::: "memory")
; #define PG8_WAIT_L(n) asm volatile("s_waitcnt lgkmcnt(" #n ")" ::: "memory")
; #define PG8_BAR __builtin_amdgcn_s_barrier()
; #define PG8_SCHED __builtin_amdgcn_sched_barrier(0)
;     __device__ __forceinline__ int nt(const pg8::Unit& u) const { return u.kind == 0 ? ntiles : q_nt(u.kind - 1); }
; template <class Epi, class Sched, bool ALIGN_EPI = true, bool SP2 = true>
; __device__ __forceinline__ void gemm_phase(PG8_LAS unsigned char* lds, const int K  , const Sched& S, const Epi& E) {
;     ...
;             const bool last = (t == nt - 2);
;             const char* a1 = cA + (size_t)(t + 1) * kstep;
;             const char* a2 = last ? nA : cA + (size_t)(t + 2) * kstep; const char* b2 = last ? nB : cB + (size_t)(t + 2) * kstep;
;             const char* a3 = a2 + kstep; const char* b3 = b2 + kstep;
;     ...
;             PG8_LDB(B0, 0, 0); PG8_LDB(B1, 0, 1); PG8_SCHED; PG8_LDA(At, 0, 0); PG8_STAGE(PG8_SA(1, 1), a1 + hstep, voffA);
;             PG8_WAIT_V(8); PG8_WAIT_L(0); PG8_BAR; PG8_MMA(0, 0, At, B0); PG8_MMA(0, 1, At, B1); PG8_BAR; PG8_SCHED;
;             PG8_LDA(At, 0, 1); PG8_STAGE(PG8_SB(0, 0), b2, voffB); PG8_STAGE(PG8_SB(0, 1), b2 + hstep, voffB); PG8_STAGE(PG8_SA(0, 0), a2, voffA);
.LBB0_2433:
	ds_read_b128 v[146:149], v152
	ds_read_b128 v[158:161], v152 offset:1024
	ds_read_b128 v[162:165], v152 offset:2048
	ds_read_b128 v[166:169], v152 offset:3072
	ds_read_b128 v[170:173], v153
	ds_read_b128 v[174:177], v153 offset:1024
	ds_read_b128 v[178:181], v153 offset:2048
	ds_read_b128 v[182:185], v153 offset:3072
	s_add_u32 s22, s20, 0xfff80080
	s_addc_u32 s23, s21, -1
	s_cmp_eq_u32 s48, 28
	s_cselect_b32 s25, s13, s23
	s_cselect_b32 s24, s44, s22
	s_cselect_b32 s23, s11, s47
	s_cselect_b32 s22, s45, s46
	v_lshl_add_u64 v[218:219], s[20:21], 0, v[138:139]
	s_add_i32 m0, s19, 0xc000
	ds_read_b128 v[186:189], v154
	ds_read_b128 v[190:193], v154 offset:1024
	ds_read_b128 v[194:197], v154 offset:2048
	ds_read_b128 v[198:201], v154 offset:3072
	ds_read_b128 v[202:205], v154 offset:4096
	ds_read_b128 v[206:209], v154 offset:5120
	ds_read_b128 v[210:213], v154 offset:6144
	ds_read_b128 v[214:217], v154 offset:7168
	global_load_lds_dwordx4 v[218:219], off
	v_lshl_add_u64 v[218:219], s[20:21], 0, v[140:141]
	s_add_i32 m0, s19, 0xe000
	s_nop 0
	global_load_lds_dwordx4 v[218:219], off
	s_waitcnt vmcnt(8)
	s_waitcnt lgkmcnt(0)
	s_barrier
	s_setprio 1
	s_waitcnt lgkmcnt(0)
	v_mfma_f32_16x16x32_bf16 v[126:129], v[146:149], v[186:189], v[126:129]
	v_mfma_f32_16x16x32_bf16 v[118:121], v[162:165], v[186:189], v[118:121]
	v_mfma_f32_16x16x32_bf16 v[110:113], v[146:149], v[194:197], v[110:113]
	v_mfma_f32_16x16x32_bf16 v[102:105], v[162:165], v[194:197], v[102:105]
	v_mfma_f32_16x16x32_bf16 v[94:97], v[146:149], v[202:205], v[94:97]
	v_mfma_f32_16x16x32_bf16 v[86:89], v[162:165], v[202:205], v[86:89]
	v_mfma_f32_16x16x32_bf16 v[78:81], v[146:149], v[210:213], v[78:81]
	v_mfma_f32_16x16x32_bf16 v[70:73], v[162:165], v[210:213], v[70:73]
	v_mfma_f32_16x16x32_bf16 v[126:129], v[158:161], v[190:193], v[126:129]
	v_mfma_f32_16x16x32_bf16 v[118:121], v[166:169], v[190:193], v[118:121]
	v_mfma_f32_16x16x32_bf16 v[110:113], v[158:161], v[198:201], v[110:113]
	v_mfma_f32_16x16x32_bf16 v[102:105], v[166:169], v[198:201], v[102:105]
	v_mfma_f32_16x16x32_bf16 v[94:97], v[158:161], v[206:209], v[94:97]
	v_mfma_f32_16x16x32_bf16 v[86:89], v[166:169], v[206:209], v[86:89]
	v_mfma_f32_16x16x32_bf16 v[78:81], v[158:161], v[214:217], v[78:81]
	v_mfma_f32_16x16x32_bf16 v[70:73], v[166:169], v[214:217], v[70:73]
	s_setprio 0
	s_setprio 1
	v_mfma_f32_16x16x32_bf16 v[122:125], v[170:173], v[186:189], v[122:125]
	v_mfma_f32_16x16x32_bf16 v[114:117], v[178:181], v[186:189], v[114:117]
	v_mfma_f32_16x16x32_bf16 v[106:109], v[170:173], v[194:197], v[106:109]
	v_mfma_f32_16x16x32_bf16 v[98:101], v[178:181], v[194:197], v[98:101]
	v_mfma_f32_16x16x32_bf16 v[90:93], v[170:173], v[202:205], v[90:93]
	v_mfma_f32_16x16x32_bf16 v[82:85], v[178:181], v[202:205], v[82:85]
	v_mfma_f32_16x16x32_bf16 v[74:77], v[170:173], v[210:213], v[74:77]
	v_mfma_f32_16x16x32_bf16 v[66:69], v[178:181], v[210:213], v[66:69]
	v_mfma_f32_16x16x32_bf16 v[122:125], v[174:177], v[190:193], v[122:125]
	v_mfma_f32_16x16x32_bf16 v[114:117], v[182:185], v[190:193], v[114:117]
	v_mfma_f32_16x16x32_bf16 v[106:109], v[174:177], v[198:201], v[106:109]
	v_mfma_f32_16x16x32_bf16 v[98:101], v[182:185], v[198:201], v[98:101]
	v_mfma_f32_16x16x32_bf16 v[90:93], v[174:177], v[206:209], v[90:93]
	v_mfma_f32_16x16x32_bf16 v[82:85], v[182:185], v[206:209], v[82:85]
	v_mfma_f32_16x16x32_bf16 v[74:77], v[174:177], v[214:217], v[74:77]
	v_mfma_f32_16x16x32_bf16 v[66:69], v[182:185], v[214:217], v[66:69]
	s_setprio 0
	s_barrier
	s_add_i32 s49, s39, s28
	v_lshl_add_u64 v[218:219], s[22:23], 0, v[134:135]
	s_mov_b32 m0, s49
	ds_read_b128 v[186:189], v154 offset:16384
	ds_read_b128 v[190:193], v154 offset:17408
	ds_read_b128 v[194:197], v154 offset:18432
	ds_read_b128 v[198:201], v154 offset:19456
	ds_read_b128 v[202:205], v154 offset:20480
	ds_read_b128 v[206:209], v154 offset:21504
	ds_read_b128 v[210:213], v154 offset:22528
	ds_read_b128 v[214:217], v154 offset:23552
	global_load_lds_dwordx4 v[218:219], off
	s_add_i32 m0, s49, 0x2000
	s_add_u32 s50, s22, 0x80000
	v_lshl_add_u64 v[220:221], s[22:23], 0, v[130:131]
	s_addc_u32 s51, s23, 0
	s_add_i32 s49, s40, s28
	global_load_lds_dwordx4 v[220:221], off
	v_lshl_add_u64 v[222:223], s[50:51], 0, v[134:135]
	s_mov_b32 m0, s49
	v_lshl_add_u64 v[224:225], s[24:25], 0, v[132:133]
	global_load_lds_dwordx4 v[222:223], off
	v_lshl_add_u64 v[222:223], s[50:51], 0, v[130:131]
	s_add_i32 m0, s49, 0x2000
	s_nop 0
	global_load_lds_dwordx4 v[222:223], off
	s_waitcnt vmcnt(6)
	s_waitcnt lgkmcnt(0)
	s_barrier
; #define PG8_STAGE(bufoff, gbase, voff) do { _Pragma("unroll") for (int _i = 0; _i < 2; ++_i) \
;         __builtin_amdgcn_global_load_lds((const unsigned*)((const char*)(gbase) + (voff)[_i]), (PG8_LAS unsigned*)(lds + (bufoff) + ldsw + _i * 8192), 16, 0, 0); } while (0)
; #define PG8_WAIT_V(n) asm volatile("s_waitcnt vmcnt(" #n ")" ::: "memory")
; #define PG8_WAIT_L(n) asm volatile("s_waitcnt lgkmcnt(" #n ")" ::: "memory")
; #define PG8_BAR __builtin_amdgcn_s_barrier()
; #define PG8_SCHED __builtin_amdgcn_sched_barrier(0)
; template <class Epi, class Sched, bool ALIGN_EPI = true, bool SP2 = true>
; __device__ __forceinline__ void gemm_phase(PG8_LAS unsigned char* lds, const int K  , const Sched& S, const Epi& E) {
;     ...
;             PG8_LDA(At, 0, 1); PG8_STAGE(PG8_SB(0, 0), b2, voffB); PG8_STAGE(PG8_SB(0, 1), b2 + hstep, voffB); PG8_STAGE(PG8_SA(0, 0), a2, voffA);
;             PG8_WAIT_V(8); PG8_WAIT_L(0); PG8_BAR; PG8_MMA(1, 0, At, B0); PG8_MMA(1, 1, At, B1); PG8_BAR; PG8_SCHED;
;             PG8_LDB(B0, 1, 0); PG8_LDB(B1, 1, 1); PG8_SCHED; PG8_LDA(At, 1, 0); PG8_STAGE(PG8_SA(0, 1), a2 + hstep, voffA);
;             PG8_WAIT_V(8); PG8_WAIT_L(0); PG8_BAR; PG8_MMA(0, 0, At, B0); PG8_MMA(0, 1, At, B1); PG8_BAR; PG8_SCHED;
	s_setprio 1
	s_waitcnt lgkmcnt(0)
	v_mfma_f32_16x16x32_bf16 v[62:65], v[146:149], v[186:189], v[62:65]
	v_mfma_f32_16x16x32_bf16 v[54:57], v[162:165], v[186:189], v[54:57]
	v_mfma_f32_16x16x32_bf16 v[46:49], v[146:149], v[194:197], v[46:49]
	v_mfma_f32_16x16x32_bf16 v[38:41], v[162:165], v[194:197], v[38:41]
	v_mfma_f32_16x16x32_bf16 v[30:33], v[146:149], v[202:205], v[30:33]
	v_mfma_f32_16x16x32_bf16 v[22:25], v[162:165], v[202:205], v[22:25]
	v_mfma_f32_16x16x32_bf16 v[14:17], v[146:149], v[210:213], v[14:17]
	v_mfma_f32_16x16x32_bf16 v[6:9], v[162:165], v[210:213], v[6:9]
	v_mfma_f32_16x16x32_bf16 v[62:65], v[158:161], v[190:193], v[62:65]
	v_mfma_f32_16x16x32_bf16 v[54:57], v[166:169], v[190:193], v[54:57]
	v_mfma_f32_16x16x32_bf16 v[46:49], v[158:161], v[198:201], v[46:49]
	v_mfma_f32_16x16x32_bf16 v[38:41], v[166:169], v[198:201], v[38:41]
	v_mfma_f32_16x16x32_bf16 v[30:33], v[158:161], v[206:209], v[30:33]
	v_mfma_f32_16x16x32_bf16 v[22:25], v[166:169], v[206:209], v[22:25]
	v_mfma_f32_16x16x32_bf16 v[14:17], v[158:161], v[214:217], v[14:17]
	v_mfma_f32_16x16x32_bf16 v[6:9], v[166:169], v[214:217], v[6:9]
	v_lshl_add_u64 v[222:223], s[24:25], 0, v[136:137]
	s_mov_b32 m0, s19
	s_nop 0
	global_load_lds_dwordx4 v[222:223], off
	s_mov_b32 m0, s31
	s_nop 0
	global_load_lds_dwordx4 v[224:225], off
	v_mfma_f32_16x16x32_bf16 v[58:61], v[170:173], v[186:189], v[58:61]
	v_mfma_f32_16x16x32_bf16 v[50:53], v[178:181], v[186:189], v[50:53]
	v_mfma_f32_16x16x32_bf16 v[42:45], v[170:173], v[194:197], v[42:45]
	v_mfma_f32_16x16x32_bf16 v[34:37], v[178:181], v[194:197], v[34:37]
	v_mfma_f32_16x16x32_bf16 v[26:29], v[170:173], v[202:205], v[26:29]
	v_mfma_f32_16x16x32_bf16 v[18:21], v[178:181], v[202:205], v[18:21]
	v_mfma_f32_16x16x32_bf16 v[10:13], v[170:173], v[210:213], v[10:13]
	v_mfma_f32_16x16x32_bf16 v[2:5], v[178:181], v[210:213], v[2:5]
	v_mfma_f32_16x16x32_bf16 v[58:61], v[174:177], v[190:193], v[58:61]
	v_mfma_f32_16x16x32_bf16 v[50:53], v[182:185], v[190:193], v[50:53]
	v_mfma_f32_16x16x32_bf16 v[42:45], v[174:177], v[198:201], v[42:45]
	v_mfma_f32_16x16x32_bf16 v[34:37], v[182:185], v[198:201], v[34:37]
	v_mfma_f32_16x16x32_bf16 v[26:29], v[174:177], v[206:209], v[26:29]
	v_mfma_f32_16x16x32_bf16 v[18:21], v[182:185], v[206:209], v[18:21]
	v_mfma_f32_16x16x32_bf16 v[10:13], v[174:177], v[214:217], v[10:13]
	v_mfma_f32_16x16x32_bf16 v[2:5], v[182:185], v[214:217], v[2:5]
	s_setprio 0
	s_barrier
	s_add_i32 s49, 0, 0x18000
	v_add_u32_e32 v157, s49, v150
	s_add_i32 s50, 0, 0x1c000
	ds_read_b128 v[146:149], v157
	ds_read_b128 v[158:161], v157 offset:1024
	ds_read_b128 v[162:165], v157 offset:2048
	ds_read_b128 v[166:169], v157 offset:3072
	v_add_u32_e32 v157, s50, v150
	ds_read_b128 v[170:173], v157
	ds_read_b128 v[174:177], v157 offset:1024
	ds_read_b128 v[178:181], v157 offset:2048
	ds_read_b128 v[182:185], v157 offset:3072
	s_add_u32 s24, s24, 0x80000
	s_addc_u32 s25, s25, 0
	s_mov_b32 m0, s33
	v_lshl_add_u64 v[226:227], s[24:25], 0, v[136:137]
	ds_read_b128 v[186:189], v154 offset:32768
	ds_read_b128 v[190:193], v154 offset:33792
	ds_read_b128 v[194:197], v154 offset:34816
	ds_read_b128 v[198:201], v154 offset:35840
	ds_read_b128 v[202:205], v154 offset:36864
	ds_read_b128 v[206:209], v154 offset:37888
	ds_read_b128 v[210:213], v154 offset:38912
	ds_read_b128 v[214:217], v154 offset:39936
	global_load_lds_dwordx4 v[226:227], off
	v_lshl_add_u64 v[226:227], s[24:25], 0, v[132:133]
	s_mov_b32 m0, s34
	s_nop 0
	global_load_lds_dwordx4 v[226:227], off
	s_waitcnt vmcnt(8)
	s_waitcnt lgkmcnt(0)
	s_barrier
	s_setprio 1
	s_waitcnt lgkmcnt(0)
	v_mfma_f32_16x16x32_bf16 v[126:129], v[146:149], v[186:189], v[126:129]
	v_mfma_f32_16x16x32_bf16 v[118:121], v[162:165], v[186:189], v[118:121]
	v_mfma_f32_16x16x32_bf16 v[110:113], v[146:149], v[194:197], v[110:113]
	v_mfma_f32_16x16x32_bf16 v[102:105], v[162:165], v[194:197], v[102:105]
	v_mfma_f32_16x16x32_bf16 v[94:97], v[146:149], v[202:205], v[94:97]
	v_mfma_f32_16x16x32_bf16 v[86:89], v[162:165], v[202:205], v[86:89]
	v_mfma_f32_16x16x32_bf16 v[78:81], v[146:149], v[210:213], v[78:81]
	v_mfma_f32_16x16x32_bf16 v[70:73], v[162:165], v[210:213], v[70:73]
	v_mfma_f32_16x16x32_bf16 v[126:129], v[158:161], v[190:193], v[126:129]
	v_mfma_f32_16x16x32_bf16 v[118:121], v[166:169], v[190:193], v[118:121]
	v_mfma_f32_16x16x32_bf16 v[110:113], v[158:161], v[198:201], v[110:113]
	v_mfma_f32_16x16x32_bf16 v[102:105], v[166:169], v[198:201], v[102:105]
	v_mfma_f32_16x16x32_bf16 v[94:97], v[158:161], v[206:209], v[94:97]
	v_mfma_f32_16x16x32_bf16 v[86:89], v[166:169], v[206:209], v[86:89]
	v_mfma_f32_16x16x32_bf16 v[78:81], v[158:161], v[214:217], v[78:81]
	v_mfma_f32_16x16x32_bf16 v[70:73], v[166:169], v[214:217], v[70:73]
	s_setprio 0
	s_setprio 1
	v_mfma_f32_16x16x32_bf16 v[122:125], v[170:173], v[186:189], v[122:125]
	v_mfma_f32_16x16x32_bf16 v[114:117], v[178:181], v[186:189], v[114:117]
	v_mfma_f32_16x16x32_bf16 v[106:109], v[170:173], v[194:197], v[106:109]
	v_mfma_f32_16x16x32_bf16 v[98:101], v[178:181], v[194:197], v[98:101]
	v_mfma_f32_16x16x32_bf16 v[90:93], v[170:173], v[202:205], v[90:93]
	v_mfma_f32_16x16x32_bf16 v[82:85], v[178:181], v[202:205], v[82:85]
	v_mfma_f32_16x16x32_bf16 v[74:77], v[170:173], v[210:213], v[74:77]
	v_mfma_f32_16x16x32_bf16 v[66:69], v[178:181], v[210:213], v[66:69]
	v_mfma_f32_16x16x32_bf16 v[122:125], v[174:177], v[190:193], v[122:125]
	v_mfma_f32_16x16x32_bf16 v[114:117], v[182:185], v[190:193], v[114:117]
	v_mfma_f32_16x16x32_bf16 v[106:109], v[174:177], v[198:201], v[106:109]
	v_mfma_f32_16x16x32_bf16 v[98:101], v[182:185], v[198:201], v[98:101]
	v_mfma_f32_16x16x32_bf16 v[90:93], v[174:177], v[206:209], v[90:93]
	v_mfma_f32_16x16x32_bf16 v[82:85], v[182:185], v[206:209], v[82:85]
	v_mfma_f32_16x16x32_bf16 v[74:77], v[174:177], v[214:217], v[74:77]
	v_mfma_f32_16x16x32_bf16 v[66:69], v[182:185], v[214:217], v[66:69]
	s_setprio 0
	s_barrier
; #define PG8_STAGE(bufoff, gbase, voff) do { _Pragma("unroll") for (int _i = 0; _i < 2; ++_i) \
;         __builtin_amdgcn_global_load_lds((const unsigned*)((const char*)(gbase) + (voff)[_i]), (PG8_LAS unsigned*)(lds + (bufoff) + ldsw + _i * 8192), 16, 0, 0); } while (0)
; #define PG8_WAIT_V(n) asm volatile("s_waitcnt vmcnt(" #n ")" ::: "memory")
; #define PG8_WAIT_L(n) asm volatile("s_waitcnt lgkmcnt(" #n ")" ::: "memory")
; #define PG8_BAR __builtin_amdgcn_s_barrier()
; #define PG8_SCHED __builtin_amdgcn_sched_barrier(0)
; template <class Epi, class Sched, bool ALIGN_EPI = true, bool SP2 = true>
; __device__ __forceinline__ void gemm_phase(PG8_LAS unsigned char* lds, const int K  , const Sched& S, const Epi& E) {
;     ...
;             PG8_LDA(At, 1, 1); PG8_STAGE(PG8_SB(1, 0), b3, voffB); PG8_STAGE(PG8_SB(1, 1), b3 + hstep, voffB); PG8_STAGE(PG8_SA(1, 0), a3, voffA);
;             PG8_WAIT_V(8); PG8_WAIT_L(0); PG8_BAR; PG8_MMA(1, 0, At, B0); PG8_MMA(1, 1, At, B1); PG8_BAR; PG8_SCHED;
;     ...
;         if constexpr (ALIGN_EPI) { if (wr == 0) PG8_BAR; }
	s_add_i32 s24, s49, s28
	v_lshl_add_u64 v[218:219], v[218:219], 0, s[6:7]
	s_mov_b32 m0, s24
	ds_read_b128 v[186:189], v154 offset:49152
	ds_read_b128 v[190:193], v154 offset:50176
	ds_read_b128 v[194:197], v154 offset:51200
	ds_read_b128 v[198:201], v154 offset:52224
	ds_read_b128 v[202:205], v154 offset:53248
	ds_read_b128 v[206:209], v154 offset:54272
	ds_read_b128 v[210:213], v154 offset:55296
	ds_read_b128 v[214:217], v154 offset:56320
	global_load_lds_dwordx4 v[218:219], off
	s_add_i32 m0, s24, 0x2000
	s_add_u32 s22, s22, 0x80080
	v_lshl_add_u64 v[218:219], v[220:221], 0, s[6:7]
	s_addc_u32 s23, s23, 0
	s_add_i32 s24, s50, s28
	global_load_lds_dwordx4 v[218:219], off
	v_lshl_add_u64 v[218:219], s[22:23], 0, v[134:135]
	s_mov_b32 m0, s24
	s_nop 0
	global_load_lds_dwordx4 v[218:219], off
	v_lshl_add_u64 v[218:219], s[22:23], 0, v[130:131]
	s_add_i32 m0, s24, 0x2000
	s_nop 0
	global_load_lds_dwordx4 v[218:219], off
	s_waitcnt vmcnt(6)
	s_waitcnt lgkmcnt(0)
	s_barrier
	s_setprio 1
	s_waitcnt lgkmcnt(0)
	v_mfma_f32_16x16x32_bf16 v[62:65], v[146:149], v[186:189], v[62:65]
	v_mfma_f32_16x16x32_bf16 v[54:57], v[162:165], v[186:189], v[54:57]
	v_mfma_f32_16x16x32_bf16 v[46:49], v[146:149], v[194:197], v[46:49]
	v_mfma_f32_16x16x32_bf16 v[38:41], v[162:165], v[194:197], v[38:41]
	v_mfma_f32_16x16x32_bf16 v[30:33], v[146:149], v[202:205], v[30:33]
	v_mfma_f32_16x16x32_bf16 v[22:25], v[162:165], v[202:205], v[22:25]
	v_mfma_f32_16x16x32_bf16 v[14:17], v[146:149], v[210:213], v[14:17]
	v_mfma_f32_16x16x32_bf16 v[6:9], v[162:165], v[210:213], v[6:9]
	v_mfma_f32_16x16x32_bf16 v[62:65], v[158:161], v[190:193], v[62:65]
	v_mfma_f32_16x16x32_bf16 v[54:57], v[166:169], v[190:193], v[54:57]
	v_mfma_f32_16x16x32_bf16 v[46:49], v[158:161], v[198:201], v[46:49]
	v_mfma_f32_16x16x32_bf16 v[38:41], v[166:169], v[198:201], v[38:41]
	v_mfma_f32_16x16x32_bf16 v[30:33], v[158:161], v[206:209], v[30:33]
	v_mfma_f32_16x16x32_bf16 v[22:25], v[166:169], v[206:209], v[22:25]
	v_mfma_f32_16x16x32_bf16 v[14:17], v[158:161], v[214:217], v[14:17]
	v_mfma_f32_16x16x32_bf16 v[6:9], v[166:169], v[214:217], v[6:9]
	v_lshl_add_u64 v[218:219], v[222:223], 0, s[6:7]
	s_mov_b32 m0, s36
	s_nop 0
	global_load_lds_dwordx4 v[218:219], off
	v_lshl_add_u64 v[218:219], v[224:225], 0, s[6:7]
	s_mov_b32 m0, s37
	s_nop 0
	global_load_lds_dwordx4 v[218:219], off
	v_mfma_f32_16x16x32_bf16 v[58:61], v[170:173], v[186:189], v[58:61]
	v_mfma_f32_16x16x32_bf16 v[50:53], v[178:181], v[186:189], v[50:53]
	v_mfma_f32_16x16x32_bf16 v[42:45], v[170:173], v[194:197], v[42:45]
	v_mfma_f32_16x16x32_bf16 v[34:37], v[178:181], v[194:197], v[34:37]
	v_mfma_f32_16x16x32_bf16 v[26:29], v[170:173], v[202:205], v[26:29]
	v_mfma_f32_16x16x32_bf16 v[18:21], v[178:181], v[202:205], v[18:21]
	v_mfma_f32_16x16x32_bf16 v[10:13], v[170:173], v[210:213], v[10:13]
	v_mfma_f32_16x16x32_bf16 v[2:5], v[178:181], v[210:213], v[2:5]
	v_mfma_f32_16x16x32_bf16 v[58:61], v[174:177], v[190:193], v[58:61]
	v_mfma_f32_16x16x32_bf16 v[50:53], v[182:185], v[190:193], v[50:53]
	v_mfma_f32_16x16x32_bf16 v[42:45], v[174:177], v[198:201], v[42:45]
	v_mfma_f32_16x16x32_bf16 v[34:37], v[182:185], v[198:201], v[34:37]
	v_mfma_f32_16x16x32_bf16 v[26:29], v[174:177], v[206:209], v[26:29]
	v_mfma_f32_16x16x32_bf16 v[18:21], v[182:185], v[206:209], v[18:21]
	v_mfma_f32_16x16x32_bf16 v[10:13], v[174:177], v[214:217], v[10:13]
	v_mfma_f32_16x16x32_bf16 v[2:5], v[182:185], v[214:217], v[2:5]
	s_setprio 0
	s_barrier
	s_add_i32 s48, s48, 2
	s_add_u32 s20, s20, 0x100
	s_addc_u32 s21, s21, 0
	s_add_u32 s46, s46, 0x100
	s_addc_u32 s47, s47, 0
	s_cmp_gt_u32 s48, 29
	s_cbranch_scc0 .LBB0_2433
	s_and_b64 vcc, exec, s[8:9]
	s_cbranch_vccz .LBB0_2436
	s_barrier
